# conv2/conv14 row prefetch one iteration ahead; LRU scan rewritten straight-line (DD/BB loaded once, kept in regs; counted waits) + XCD-aware item remap
# speedup vs baseline: 1.0220x; 1.0220x over previous
; __device__ __forceinline__ unsigned cvt_pk_bf16(float lo, float hi) { unsigned r; asm volatile("v_cvt_pk_bf16_f32 %0, %1, %2" : "=v"(r) : "v"(lo), "v"(hi)); return r; }
; __device__ __forceinline__ float bflo(unsigned w) { return __uint_as_float(w << 16); }
; __device__ __forceinline__ float bfhi(unsigned w) { return __uint_as_float(w & 0xffff0000u); }
; __device__ __forceinline__ float fsilu(float x) { return x * fsigmoid(x); }
; template <bool SILU>
; __device__ __forceinline__ void conv_phase(const bf16_t* src, const float* w, const float* b, bf16_t* dst, int C, int gt, int NGT) {
;     ...
;         const bool head = (row0 & (SEQ - 1)) == 0;
;         const bf16_t* sp = src + (size_t)row0 * C + c0;
;         u32x4 x0, x1, x2;
;         if (head) { x0 = (u32x4){0u, 0u, 0u, 0u}; x1 = x0; x2 = x0; }
;         else { x0 = *(const u32x4*)(sp - (size_t)3 * C); x1 = *(const u32x4*)(sp - (size_t)2 * C); x2 = *(const u32x4*)(sp - (size_t)C); }
; #pragma unroll 4
;         for (int r = 0; r < 16; ++r) {
;             const u32x4 x3 = *(const u32x4*)(sp + (size_t)r * C);
;             const unsigned xa[4][4] = {{x0.x, x0.y, x0.z, x0.w}, {x1.x, x1.y, x1.z, x1.w}, {x2.x, x2.y, x2.z, x2.w}, {x3.x, x3.y, x3.z, x3.w}};
;             float a[8];
; #pragma unroll
;             for (int j = 0; j < 8; ++j) a[j] = bs[j];
; #pragma unroll
;             for (int k = 0; k < 4; ++k)
; #pragma unroll
;                 for (int q = 0; q < 4; ++q) { a[2 * q] += wt[k][2 * q] * bflo(xa[k][q]); a[2 * q + 1] += wt[k][2 * q + 1] * bfhi(xa[k][q]); }
;             if (SILU) {
; #pragma unroll
;                 for (int j = 0; j < 8; ++j) a[j] = fsilu(a[j]); }
;             u32x4 o; o.x = cvt_pk_bf16(a[0], a[1]); o.y = cvt_pk_bf16(a[2], a[3]); o.z = cvt_pk_bf16(a[4], a[5]); o.w = cvt_pk_bf16(a[6], a[7]);
;             *(u32x4*)(dst + (size_t)(row0 + r) * C + c0) = o;
.LBB0_153:
	s_or_b64 exec, exec, s[14:15]
	v_lshl_add_u64 v[112:113], s[6:7], 0, v[60:61]
	v_lshl_add_u64 v[112:113], v[58:59], 1, v[112:113]
	global_load_dwordx4 v[94:97], v[112:113], off
	v_add_co_u32_e32 v112, vcc, 0x3000, v112
	s_nop 1
	v_addc_co_u32_e32 v113, vcc, 0, v113, vcc
	global_load_dwordx4 v[98:101], v[112:113], off
	v_add_co_u32_e32 v112, vcc, 0x3000, v112
	s_nop 1
	v_addc_co_u32_e32 v113, vcc, 0, v113, vcc
	global_load_dwordx4 v[102:105], v[112:113], off
	v_add_co_u32_e32 v112, vcc, 0x3000, v112
	s_nop 1
	v_addc_co_u32_e32 v113, vcc, 0, v113, vcc
	global_load_dwordx4 v[106:109], v[112:113], off
	s_waitcnt vmcnt(0)
	v_mov_b32_e32 v56, v48
	v_mov_b32_e32 v57, v12
	v_mov_b32_e32 v12, v49
	v_mov_b32_e32 v48, v40
	v_mov_b32_e32 v49, v8
	v_mov_b32_e32 v8, v41
	v_lshl_add_u64 v[40:41], v[58:59], 1, v[60:61]
	s_waitcnt vmcnt(2)
	v_mov_b32_e32 v2, v54
	v_mov_b32_e32 v3, v18
	v_mov_b32_e32 v18, v55
	v_mov_b32_e32 v54, v46
	v_mov_b32_e32 v55, v6
	v_mov_b32_e32 v6, v47
	v_mov_b32_e32 v46, v52
	v_mov_b32_e32 v47, v16
	v_mov_b32_e32 v16, v53
	v_mov_b32_e32 v52, v44
	v_mov_b32_e32 v53, v4
	v_mov_b32_e32 v4, v45
	v_mov_b32_e32 v44, v50
	v_mov_b32_e32 v45, v14
	v_mov_b32_e32 v14, v51
	v_mov_b32_e32 v50, v42
	v_mov_b32_e32 v51, v10
	v_mov_b32_e32 v10, v43
	v_lshl_add_u64 v[58:59], s[18:19], 0, v[40:41]
	s_mov_b64 s[14:15], 0
.LBB0_154:
	v_lshl_add_u64 v[60:61], v[58:59], 0, s[14:15]
	v_add_co_u32_e32 v40, vcc, 0x14c00000, v60
	v_lshlrev_b32_e32 v71, 16, v28
	s_nop 0
	v_addc_co_u32_e32 v41, vcc, 0, v61, vcc
	v_lshlrev_b32_e32 v70, 16, v32
	v_pk_mul_f32 v[62:63], v[48:49], v[70:71]
	v_and_b32_e32 v73, 0xffff0000, v28
	v_add_f32_e32 v1, v24, v63
	v_and_b32_e32 v72, 0xffff0000, v32
	v_add_f32_e32 v1, v62, v1
	v_pk_mul_f32 v[62:63], v[8:9], v[72:73]
	v_lshlrev_b32_e32 v75, 16, v29
	v_add_f32_e32 v28, v25, v63
	v_lshlrev_b32_e32 v74, 16, v33
	v_add_f32_e32 v66, v62, v28
	v_pk_mul_f32 v[62:63], v[50:51], v[74:75]
	v_and_b32_e32 v77, 0xffff0000, v29
	v_add_f32_e32 v28, v26, v63
	v_and_b32_e32 v76, 0xffff0000, v33
	v_add_f32_e32 v68, v62, v28
	v_pk_mul_f32 v[28:29], v[10:11], v[76:77]
	v_lshlrev_b32_e32 v33, 16, v30
	v_add_f32_e32 v29, v27, v29
	v_lshlrev_b32_e32 v32, 16, v34
	v_add_f32_e32 v69, v28, v29
	v_pk_mul_f32 v[28:29], v[52:53], v[32:33]
	v_and_b32_e32 v79, 0xffff0000, v30
	v_add_f32_e32 v29, v20, v29
	v_and_b32_e32 v78, 0xffff0000, v34
	v_add_f32_e32 v33, v28, v29
	v_pk_mul_f32 v[28:29], v[4:5], v[78:79]
	v_lshlrev_b32_e32 v81, 16, v31
	v_add_f32_e32 v29, v21, v29
	v_lshlrev_b32_e32 v80, 16, v35
	v_add_f32_e32 v30, v28, v29
	v_pk_mul_f32 v[28:29], v[54:55], v[80:81]
	v_and_b32_e32 v87, 0xffff0000, v31
	v_add_f32_e32 v29, v22, v29
	v_and_b32_e32 v86, 0xffff0000, v35
	v_add_f32_e32 v34, v28, v29
	v_pk_mul_f32 v[28:29], v[6:7], v[86:87]
	v_lshlrev_b32_e32 v63, 16, v36
	v_add_f32_e32 v29, v23, v29
	v_add_f32_e32 v31, v28, v29
	v_and_b32_e32 v65, 0xffff0000, v36
	v_lshlrev_b32_e32 v67, 16, v37
	v_and_b32_e32 v37, 0xffff0000, v37
	v_and_b32_e32 v83, 0xffff0000, v38
	v_lshlrev_b32_e32 v85, 16, v39
	v_and_b32_e32 v39, 0xffff0000, v39
	s_mov_b32 s16, 0x1ac00000
	s_add_u32 s14, s14, 0xc000
	s_addc_u32 s15, s15, 0
	s_cmp_eq_u32 s14, 0x30000
	s_cbranch_scc1 .Lcv14_last0
	s_waitcnt vmcnt(7)
	v_mov_b64_e32 v[40:41], v[94:95]
	v_mov_b64_e32 v[42:43], v[96:97]
	v_add_co_u32_e32 v112, vcc, 0x14c0c000, v60
	s_nop 1
	v_addc_co_u32_e32 v113, vcc, 0, v61, vcc
	global_load_dwordx4 v[94:97], v[112:113], off
	s_branch .Lcv14_join0
.Lcv14_last0:
	s_waitcnt vmcnt(7)
	v_mov_b64_e32 v[40:41], v[94:95]
	v_mov_b64_e32 v[42:43], v[96:97]
.Lcv14_join0:
	v_lshlrev_b32_e32 v62, 16, v40
	v_pk_mul_f32 v[28:29], v[56:57], v[62:63]
	v_and_b32_e32 v64, 0xffff0000, v40
	v_add_f32_e32 v1, v29, v1
	v_add_f32_e32 v1, v28, v1
	v_pk_mul_f32 v[28:29], v[12:13], v[64:65]
	v_and_b32_e32 v36, 0xffff0000, v41
	v_add_f32_e32 v29, v29, v66
	v_lshlrev_b32_e32 v66, 16, v41
	v_add_f32_e32 v35, v28, v29
	v_pk_mul_f32 v[28:29], v[44:45], v[66:67]
	v_and_b32_e32 v82, 0xffff0000, v42
	v_add_f32_e32 v29, v29, v68
	v_add_f32_e32 v40, v28, v29
	v_pk_mul_f32 v[28:29], v[14:15], v[36:37]
	v_lshlrev_b32_e32 v68, 16, v42
	v_add_f32_e32 v29, v29, v69
	v_lshlrev_b32_e32 v69, 16, v38
	v_add_f32_e32 v41, v28, v29
	v_pk_mul_f32 v[28:29], v[46:47], v[68:69]
	v_lshlrev_b32_e32 v84, 16, v43
	v_add_f32_e32 v29, v29, v33
	v_add_f32_e32 v33, v28, v29
	v_pk_mul_f32 v[28:29], v[16:17], v[82:83]
	v_and_b32_e32 v38, 0xffff0000, v43
	v_add_f32_e32 v29, v29, v30
	v_add_f32_e32 v30, v28, v29
	v_pk_mul_f32 v[28:29], v[2:3], v[84:85]
	v_mov_b32_e32 v43, v64
	v_add_f32_e32 v29, v29, v34
	v_add_f32_e32 v34, v28, v29
	v_pk_mul_f32 v[28:29], v[18:19], v[38:39]
	v_mov_b32_e32 v71, v66
	v_add_f32_e32 v29, v29, v31
	v_mul_f32_e32 v31, 0xbfb8aa3b, v40
	v_exp_f32_e32 v31, v31
	v_add_f32_e32 v28, v28, v29
	v_mul_f32_e32 v29, 0xbfb8aa3b, v1
	v_exp_f32_e32 v29, v29
	v_add_f32_e32 v31, 1.0, v31
	v_rcp_f32_e32 v31, v31
	v_mov_b32_e32 v73, v36
	v_add_f32_e32 v29, 1.0, v29
	v_rcp_f32_e32 v29, v29
	v_mul_f32_e32 v31, v40, v31
	v_mul_f32_e32 v40, 0xbfb8aa3b, v33
	v_exp_f32_e32 v40, v40
	v_mul_f32_e32 v1, v1, v29
	v_mul_f32_e32 v29, 0xbfb8aa3b, v35
	v_exp_f32_e32 v29, v29
	v_add_f32_e32 v40, 1.0, v40
	v_rcp_f32_e32 v40, v40
	v_mov_b32_e32 v75, v68
	v_add_f32_e32 v29, 1.0, v29
	v_rcp_f32_e32 v29, v29
	v_mul_f32_e32 v33, v33, v40
	v_mul_f32_e32 v40, 0xbfb8aa3b, v30
	v_exp_f32_e32 v40, v40
	v_mul_f32_e32 v29, v35, v29
	v_mul_f32_e32 v35, 0xbfb8aa3b, v41
	v_exp_f32_e32 v35, v35
	v_add_f32_e32 v40, 1.0, v40
	v_rcp_f32_e32 v40, v40
	v_mov_b32_e32 v77, v82
	v_add_f32_e32 v35, 1.0, v35
	v_rcp_f32_e32 v35, v35
	v_mul_f32_e32 v30, v30, v40
; __device__ __forceinline__ unsigned cvt_pk_bf16(float lo, float hi) { unsigned r; asm volatile("v_cvt_pk_bf16_f32 %0, %1, %2" : "=v"(r) : "v"(lo), "v"(hi)); return r; }
; __device__ __forceinline__ float bflo(unsigned w) { return __uint_as_float(w << 16); }
; __device__ __forceinline__ float bfhi(unsigned w) { return __uint_as_float(w & 0xffff0000u); }
; __device__ __forceinline__ float fsilu(float x) { return x * fsigmoid(x); }
; template <bool SILU>
; __device__ __forceinline__ void conv_phase(const bf16_t* src, const float* w, const float* b, bf16_t* dst, int C, int gt, int NGT) {
;     ...
;         for (int r = 0; r < 16; ++r) {
;             const u32x4 x3 = *(const u32x4*)(sp + (size_t)r * C);
;             const unsigned xa[4][4] = {{x0.x, x0.y, x0.z, x0.w}, {x1.x, x1.y, x1.z, x1.w}, {x2.x, x2.y, x2.z, x2.w}, {x3.x, x3.y, x3.z, x3.w}};
;             float a[8];
; #pragma unroll
;             for (int j = 0; j < 8; ++j) a[j] = bs[j];
; #pragma unroll
;             for (int k = 0; k < 4; ++k)
; #pragma unroll
;                 for (int q = 0; q < 4; ++q) { a[2 * q] += wt[k][2 * q] * bflo(xa[k][q]); a[2 * q + 1] += wt[k][2 * q + 1] * bfhi(xa[k][q]); }
;             if (SILU) {
; #pragma unroll
;                 for (int j = 0; j < 8; ++j) a[j] = fsilu(a[j]); }
;             u32x4 o; o.x = cvt_pk_bf16(a[0], a[1]); o.y = cvt_pk_bf16(a[2], a[3]); o.z = cvt_pk_bf16(a[4], a[5]); o.w = cvt_pk_bf16(a[6], a[7]);
;             *(u32x4*)(dst + (size_t)(row0 + r) * C + c0) = o;
	v_mul_f32_e32 v40, 0xbfb8aa3b, v34
	v_exp_f32_e32 v40, v40
	v_mul_f32_e32 v35, v41, v35
	v_mov_b32_e32 v41, v62
	v_mov_b32_e32 v79, v84
	v_add_f32_e32 v40, 1.0, v40
	v_rcp_f32_e32 v40, v40
	v_mov_b32_e32 v81, v38
	v_mul_f32_e32 v34, v34, v40
	v_mul_f32_e32 v40, 0xbfb8aa3b, v28
	v_exp_f32_e32 v40, v40
	s_nop 0
	v_add_f32_e32 v40, 1.0, v40
	v_rcp_f32_e32 v40, v40
	s_nop 0
	v_mul_f32_e32 v40, v28, v40
	v_cvt_pk_bf16_f32 v28, v1, v29
	v_cvt_pk_bf16_f32 v29, v31, v35
	v_cvt_pk_bf16_f32 v30, v33, v30
	v_cvt_pk_bf16_f32 v31, v34, v40
	v_add_co_u32_e32 v34, vcc, s16, v60
	s_mov_b32 s16, 0x14c03000
	s_nop 0
	v_addc_co_u32_e32 v35, vcc, 0, v61, vcc
	global_store_dwordx4 v[34:35], v[28:31], off
	v_mov_b32_e32 v34, v63
	v_mov_b32_e32 v35, v70
	v_add_co_u32_e32 v28, vcc, s16, v60
	v_pk_mul_f32 v[34:35], v[48:49], v[34:35]
	s_nop 0
	v_addc_co_u32_e32 v29, vcc, 0, v61, vcc
	v_add_f32_e32 v1, v24, v35
	v_add_f32_e32 v1, v34, v1
	v_mov_b32_e32 v34, v65
	v_mov_b32_e32 v35, v72
	v_pk_mul_f32 v[34:35], v[8:9], v[34:35]
	s_mov_b32 s16, 0x14c06000
	v_add_f32_e32 v33, v25, v35
	v_add_f32_e32 v70, v34, v33
	v_mov_b32_e32 v34, v67
	v_mov_b32_e32 v35, v74
	v_pk_mul_f32 v[34:35], v[50:51], v[34:35]
	v_pk_mul_f32 v[62:63], v[48:49], v[62:63]
	v_add_f32_e32 v33, v26, v35
	v_add_f32_e32 v72, v34, v33
	v_mov_b32_e32 v34, v37
	v_mov_b32_e32 v35, v76
	v_pk_mul_f32 v[34:35], v[10:11], v[34:35]
	v_pk_mul_f32 v[36:37], v[10:11], v[36:37]
	v_add_f32_e32 v33, v27, v35
	v_add_f32_e32 v74, v34, v33
	v_mov_b32_e32 v34, v69
	v_mov_b32_e32 v35, v32
	v_pk_mul_f32 v[32:33], v[52:53], v[34:35]
	v_add_f32_e32 v37, v27, v37
	v_add_f32_e32 v33, v20, v33
	v_add_f32_e32 v34, v32, v33
	v_mov_b32_e32 v32, v83
	v_mov_b32_e32 v33, v78
	v_pk_mul_f32 v[32:33], v[4:5], v[32:33]
	s_cbranch_scc1 .Lcv14_last1
	s_waitcnt vmcnt(7)
	v_mov_b64_e32 v[28:29], v[98:99]
	v_mov_b64_e32 v[30:31], v[100:101]
	v_add_co_u32_e32 v112, vcc, 0x3000, v112
	s_nop 1
	v_addc_co_u32_e32 v113, vcc, 0, v113, vcc
	global_load_dwordx4 v[98:101], v[112:113], off
	s_branch .Lcv14_join1
.Lcv14_last1:
	s_waitcnt vmcnt(6)
	v_mov_b64_e32 v[28:29], v[98:99]
	v_mov_b64_e32 v[30:31], v[100:101]
.Lcv14_join1:
	v_lshlrev_b32_e32 v40, 16, v28
	v_add_f32_e32 v33, v21, v33
	v_add_f32_e32 v35, v32, v33
	v_mov_b32_e32 v32, v85
	v_mov_b32_e32 v33, v80
	v_pk_mul_f32 v[32:33], v[54:55], v[32:33]
	v_and_b32_e32 v42, 0xffff0000, v28
	v_add_f32_e32 v33, v22, v33
	v_add_f32_e32 v80, v32, v33
	v_mov_b32_e32 v32, v39
	v_mov_b32_e32 v33, v86
	v_pk_mul_f32 v[32:33], v[6:7], v[32:33]
	v_and_b32_e32 v76, 0xffff0000, v30
	v_add_f32_e32 v33, v23, v33
	v_add_f32_e32 v86, v32, v33
	v_pk_mul_f32 v[32:33], v[56:57], v[40:41]
	v_lshlrev_b32_e32 v78, 16, v31
	v_add_f32_e32 v1, v33, v1
	v_add_f32_e32 v1, v32, v1
	v_pk_mul_f32 v[32:33], v[12:13], v[42:43]
	s_nop 0
	v_add_f32_e32 v33, v33, v70
	v_lshlrev_b32_e32 v70, 16, v29
	v_add_f32_e32 v87, v32, v33
	v_pk_mul_f32 v[32:33], v[44:45], v[70:71]
	s_nop 0
	v_add_f32_e32 v33, v33, v72
	v_and_b32_e32 v72, 0xffff0000, v29
	v_add_f32_e32 v89, v32, v33
	v_pk_mul_f32 v[32:33], v[14:15], v[72:73]
	s_nop 0
	v_add_f32_e32 v33, v33, v74
	v_lshlrev_b32_e32 v74, 16, v30
	v_add_f32_e32 v90, v32, v33
	v_pk_mul_f32 v[32:33], v[46:47], v[74:75]
	s_nop 0
	v_add_f32_e32 v33, v33, v34
	v_add_f32_e32 v34, v32, v33
	v_pk_mul_f32 v[32:33], v[16:17], v[76:77]
	s_nop 0
	v_add_f32_e32 v33, v33, v35
	v_add_f32_e32 v35, v32, v33
	v_pk_mul_f32 v[32:33], v[2:3], v[78:79]
	s_nop 0
	v_add_f32_e32 v33, v33, v80
	v_and_b32_e32 v80, 0xffff0000, v31
	v_add_f32_e32 v91, v32, v33
	v_pk_mul_f32 v[32:33], v[18:19], v[80:81]
	s_nop 0
	v_add_f32_e32 v33, v33, v86
	v_add_f32_e32 v32, v32, v33
	v_mul_f32_e32 v33, 0xbfb8aa3b, v1
	v_exp_f32_e32 v33, v33
	v_mul_f32_e32 v86, 0xbfb8aa3b, v89
	v_exp_f32_e32 v86, v86
	v_add_f32_e32 v33, 1.0, v33
	v_rcp_f32_e32 v33, v33
	v_add_f32_e32 v86, 1.0, v86
	v_rcp_f32_e32 v86, v86
	v_mul_f32_e32 v1, v1, v33
	v_mul_f32_e32 v33, 0xbfb8aa3b, v87
	v_exp_f32_e32 v33, v33
	v_mul_f32_e32 v86, v89, v86
	v_mul_f32_e32 v89, 0xbfb8aa3b, v34
	v_exp_f32_e32 v89, v89
	v_add_f32_e32 v33, 1.0, v33
	v_rcp_f32_e32 v33, v33
	v_add_f32_e32 v89, 1.0, v89
	v_rcp_f32_e32 v89, v89
	v_mul_f32_e32 v33, v87, v33
	v_mul_f32_e32 v87, 0xbfb8aa3b, v90
	v_exp_f32_e32 v87, v87
	v_mul_f32_e32 v34, v34, v89
	v_mul_f32_e32 v89, 0xbfb8aa3b, v35
	v_exp_f32_e32 v89, v89
	v_add_f32_e32 v87, 1.0, v87
	v_rcp_f32_e32 v87, v87
	v_add_f32_e32 v89, 1.0, v89
	v_rcp_f32_e32 v89, v89
	v_mul_f32_e32 v87, v90, v87
	v_mul_f32_e32 v90, 0xbfb8aa3b, v32
	v_exp_f32_e32 v90, v90
	v_mul_f32_e32 v35, v35, v89
	v_mul_f32_e32 v89, 0xbfb8aa3b, v91
	v_exp_f32_e32 v89, v89
	v_add_f32_e32 v90, 1.0, v90
	v_rcp_f32_e32 v90, v90
	v_add_f32_e32 v89, 1.0, v89
	v_rcp_f32_e32 v89, v89
	v_mul_f32_e32 v90, v32, v90
	v_cvt_pk_bf16_f32 v32, v1, v33
	v_cvt_pk_bf16_f32 v33, v86, v87
	v_add_co_u32_e32 v86, vcc, s87, v60
	v_mul_f32_e32 v89, v91, v89
	s_nop 0
	v_addc_co_u32_e32 v87, vcc, 0, v61, vcc
	v_cvt_pk_bf16_f32 v34, v34, v35
	v_cvt_pk_bf16_f32 v35, v89, v90
	global_store_dwordx4 v[86:87], v[32:35], off
	v_add_f32_e32 v89, v36, v37
	v_pk_mul_f32 v[36:37], v[52:53], v[68:69]
	v_add_co_u32_e32 v32, vcc, s16, v60
	v_add_f32_e32 v37, v20, v37
	s_nop 0
	v_addc_co_u32_e32 v33, vcc, 0, v61, vcc
	v_add_f32_e32 v1, v24, v63
	v_add_f32_e32 v90, v36, v37
	v_pk_mul_f32 v[36:37], v[4:5], v[82:83]
	v_add_f32_e32 v1, v62, v1
	v_pk_mul_f32 v[62:63], v[8:9], v[64:65]
	v_add_f32_e32 v37, v21, v37
	v_add_f32_e32 v63, v25, v63
	v_add_f32_e32 v91, v36, v37
	v_pk_mul_f32 v[36:37], v[54:55], v[84:85]
	v_add_f32_e32 v86, v62, v63
	v_pk_mul_f32 v[62:63], v[50:51], v[66:67]
	v_add_f32_e32 v37, v22, v37
	v_add_f32_e32 v63, v26, v63
	v_add_f32_e32 v92, v36, v37
	v_pk_mul_f32 v[36:37], v[6:7], v[38:39]
	v_add_f32_e32 v87, v62, v63
	v_add_f32_e32 v37, v23, v37
	v_mov_b32_e32 v63, v40
	v_add_f32_e32 v38, v36, v37
	v_mov_b32_e32 v65, v42
	v_mov_b32_e32 v67, v70
	v_mov_b32_e32 v69, v72
	v_mov_b32_e32 v83, v74
	v_mov_b32_e32 v85, v76
	s_mov_b32 s16, 0x14c09000
	v_pk_mul_f32 v[40:41], v[48:49], v[40:41]
	s_cbranch_scc1 .Lcv14_last2
	s_waitcnt vmcnt(7)
	v_mov_b64_e32 v[32:33], v[102:103]
	v_mov_b64_e32 v[34:35], v[104:105]
	v_add_co_u32_e32 v112, vcc, 0x3000, v112
	s_nop 1
	v_addc_co_u32_e32 v113, vcc, 0, v113, vcc
	global_load_dwordx4 v[102:105], v[112:113], off
	s_branch .Lcv14_join2
; __device__ __forceinline__ unsigned cvt_pk_bf16(float lo, float hi) { unsigned r; asm volatile("v_cvt_pk_bf16_f32 %0, %1, %2" : "=v"(r) : "v"(lo), "v"(hi)); return r; }
; __device__ __forceinline__ float bflo(unsigned w) { return __uint_as_float(w << 16); }
; __device__ __forceinline__ float bfhi(unsigned w) { return __uint_as_float(w & 0xffff0000u); }
; __device__ __forceinline__ float fsilu(float x) { return x * fsigmoid(x); }
; template <bool SILU>
; __device__ __forceinline__ void conv_phase(const bf16_t* src, const float* w, const float* b, bf16_t* dst, int C, int gt, int NGT) {
;     ...
;         for (int r = 0; r < 16; ++r) {
;             const u32x4 x3 = *(const u32x4*)(sp + (size_t)r * C);
;             const unsigned xa[4][4] = {{x0.x, x0.y, x0.z, x0.w}, {x1.x, x1.y, x1.z, x1.w}, {x2.x, x2.y, x2.z, x2.w}, {x3.x, x3.y, x3.z, x3.w}};
;             float a[8];
; #pragma unroll
;             for (int j = 0; j < 8; ++j) a[j] = bs[j];
; #pragma unroll
;             for (int k = 0; k < 4; ++k)
; #pragma unroll
;                 for (int q = 0; q < 4; ++q) { a[2 * q] += wt[k][2 * q] * bflo(xa[k][q]); a[2 * q + 1] += wt[k][2 * q + 1] * bfhi(xa[k][q]); }
;             if (SILU) {
; #pragma unroll
;                 for (int j = 0; j < 8; ++j) a[j] = fsilu(a[j]); }
;             u32x4 o; o.x = cvt_pk_bf16(a[0], a[1]); o.y = cvt_pk_bf16(a[2], a[3]); o.z = cvt_pk_bf16(a[4], a[5]); o.w = cvt_pk_bf16(a[6], a[7]);
;             *(u32x4*)(dst + (size_t)(row0 + r) * C + c0) = o;
.Lcv14_last2:
	s_waitcnt vmcnt(5)
	v_mov_b64_e32 v[32:33], v[102:103]
	v_mov_b64_e32 v[34:35], v[104:105]
.Lcv14_join2:
	v_lshlrev_b32_e32 v62, 16, v32
	v_pk_mul_f32 v[36:37], v[56:57], v[62:63]
	v_and_b32_e32 v64, 0xffff0000, v32
	v_add_f32_e32 v1, v37, v1
	v_add_f32_e32 v1, v36, v1
	v_pk_mul_f32 v[36:37], v[12:13], v[64:65]
	v_lshlrev_b32_e32 v66, 16, v33
	v_add_f32_e32 v37, v37, v86
	v_add_f32_e32 v39, v36, v37
	v_pk_mul_f32 v[36:37], v[44:45], v[66:67]
	v_and_b32_e32 v68, 0xffff0000, v33
	v_add_f32_e32 v37, v37, v87
	v_add_f32_e32 v63, v36, v37
	v_pk_mul_f32 v[36:37], v[14:15], v[68:69]
	v_lshlrev_b32_e32 v82, 16, v34
	v_add_f32_e32 v37, v37, v89
	v_add_f32_e32 v65, v36, v37
	v_pk_mul_f32 v[36:37], v[46:47], v[82:83]
	v_and_b32_e32 v84, 0xffff0000, v34
	v_add_f32_e32 v37, v37, v90
	v_add_f32_e32 v67, v36, v37
	v_pk_mul_f32 v[36:37], v[16:17], v[84:85]
	v_lshlrev_b32_e32 v86, 16, v35
	v_add_f32_e32 v37, v37, v91
	v_mov_b32_e32 v87, v78
	v_add_f32_e32 v69, v36, v37
	v_pk_mul_f32 v[36:37], v[2:3], v[86:87]
	v_and_b32_e32 v90, 0xffff0000, v35
	v_add_f32_e32 v37, v37, v92
	v_mov_b32_e32 v91, v80
	v_add_f32_e32 v83, v36, v37
	v_pk_mul_f32 v[36:37], v[18:19], v[90:91]
	v_add_co_u32_e32 v92, vcc, s88, v60
	v_add_f32_e32 v37, v37, v38
	v_add_f32_e32 v36, v36, v37
	v_mul_f32_e32 v37, 0xbfb8aa3b, v1
	v_exp_f32_e32 v37, v37
	v_mul_f32_e32 v38, 0xbfb8aa3b, v63
	v_exp_f32_e32 v38, v38
	v_addc_co_u32_e32 v93, vcc, 0, v61, vcc
	v_add_f32_e32 v37, 1.0, v37
	v_rcp_f32_e32 v37, v37
	v_add_f32_e32 v38, 1.0, v38
	v_rcp_f32_e32 v38, v38
	v_mul_f32_e32 v1, v1, v37
	v_mul_f32_e32 v37, 0xbfb8aa3b, v39
	v_exp_f32_e32 v37, v37
	v_mul_f32_e32 v38, v63, v38
	v_mul_f32_e32 v63, 0xbfb8aa3b, v67
	v_exp_f32_e32 v63, v63
	v_add_f32_e32 v37, 1.0, v37
	v_rcp_f32_e32 v37, v37
	v_add_f32_e32 v63, 1.0, v63
	v_rcp_f32_e32 v63, v63
	v_mul_f32_e32 v37, v39, v37
	v_mul_f32_e32 v39, 0xbfb8aa3b, v65
	v_exp_f32_e32 v39, v39
	v_mul_f32_e32 v63, v67, v63
	v_mul_f32_e32 v67, 0xbfb8aa3b, v83
	v_exp_f32_e32 v67, v67
	v_add_f32_e32 v39, 1.0, v39
	v_rcp_f32_e32 v39, v39
	v_add_f32_e32 v67, 1.0, v67
	v_rcp_f32_e32 v67, v67
	v_mul_f32_e32 v39, v65, v39
	v_mul_f32_e32 v65, 0xbfb8aa3b, v69
	v_exp_f32_e32 v65, v65
	v_mul_f32_e32 v67, v83, v67
	v_add_f32_e32 v65, 1.0, v65
	v_rcp_f32_e32 v65, v65
	s_nop 0
	v_mul_f32_e32 v65, v69, v65
	v_mul_f32_e32 v69, 0xbfb8aa3b, v36
	v_exp_f32_e32 v69, v69
	s_nop 0
	v_add_f32_e32 v69, 1.0, v69
	v_rcp_f32_e32 v69, v69
	s_nop 0
	v_mul_f32_e32 v69, v36, v69
	v_cvt_pk_bf16_f32 v36, v1, v37
	v_cvt_pk_bf16_f32 v37, v38, v39
	v_cvt_pk_bf16_f32 v38, v63, v65
	v_cvt_pk_bf16_f32 v39, v67, v69
	global_store_dwordx4 v[92:93], v[36:39], off
	v_add_f32_e32 v1, v24, v41
	v_add_f32_e32 v1, v40, v1
	v_add_co_u32_e32 v36, vcc, s16, v60
	v_pk_mul_f32 v[40:41], v[8:9], v[42:43]
	s_nop 0
	v_addc_co_u32_e32 v37, vcc, 0, v61, vcc
	v_add_f32_e32 v41, v25, v41
	v_add_f32_e32 v42, v40, v41
	v_pk_mul_f32 v[40:41], v[50:51], v[70:71]
	v_add_co_u32_e32 v60, vcc, 0x1ac09000, v60
	v_add_f32_e32 v41, v26, v41
	v_add_f32_e32 v43, v40, v41
	v_pk_mul_f32 v[40:41], v[10:11], v[72:73]
	v_addc_co_u32_e32 v61, vcc, 0, v61, vcc
	v_add_f32_e32 v41, v27, v41
	v_add_f32_e32 v63, v40, v41
	v_pk_mul_f32 v[40:41], v[52:53], v[74:75]
	s_nop 0
	v_add_f32_e32 v41, v20, v41
	v_add_f32_e32 v65, v40, v41
	v_pk_mul_f32 v[40:41], v[4:5], v[76:77]
	s_nop 0
	v_add_f32_e32 v41, v21, v41
	v_add_f32_e32 v67, v40, v41
	v_pk_mul_f32 v[40:41], v[54:55], v[78:79]
	s_nop 0
	v_add_f32_e32 v41, v22, v41
	v_add_f32_e32 v69, v40, v41
	v_pk_mul_f32 v[40:41], v[6:7], v[80:81]
	s_nop 0
	v_add_f32_e32 v41, v23, v41
	v_add_f32_e32 v70, v40, v41
	v_mov_b32_e32 v41, v62
	s_cbranch_scc1 .Lcv14_last3
	s_waitcnt vmcnt(7)
	v_mov_b64_e32 v[36:37], v[106:107]
	v_mov_b64_e32 v[38:39], v[108:109]
	v_add_co_u32_e32 v112, vcc, 0x3000, v112
	s_nop 1
	v_addc_co_u32_e32 v113, vcc, 0, v113, vcc
	global_load_dwordx4 v[106:109], v[112:113], off
	s_branch .Lcv14_join3
; __device__ __forceinline__ unsigned cvt_pk_bf16(float lo, float hi) { unsigned r; asm volatile("v_cvt_pk_bf16_f32 %0, %1, %2" : "=v"(r) : "v"(lo), "v"(hi)); return r; }
; template <bool SILU>
; __device__ __forceinline__ void conv_phase(const bf16_t* src, const float* w, const float* b, bf16_t* dst, int C, int gt, int NGT) {
;     ...
;     for (int it = gt; it < nitems; it += NGT) {
;         const int rb = it / c8n, c0 = (it % c8n) * 8, row0 = rb * 16;
;         float wt[4][8], bs[8];
; #pragma unroll
;         for (int k = 0; k < 4; ++k) { const f32x4 w0 = *(const f32x4*)(w + (size_t)k * C + c0), w1 = *(const f32x4*)(w + (size_t)k * C + c0 + 4);
;             wt[k][0] = w0[0]; wt[k][1] = w0[1]; wt[k][2] = w0[2]; wt[k][3] = w0[3]; wt[k][4] = w1[0]; wt[k][5] = w1[1]; wt[k][6] = w1[2]; wt[k][7] = w1[3]; }
;         { const f32x4 b0 = *(const f32x4*)(b + c0), b1 = *(const f32x4*)(b + c0 + 4); bs[0] = b0[0]; bs[1] = b0[1]; bs[2] = b0[2]; bs[3] = b0[3]; bs[4] = b1[0]; bs[5] = b1[1]; bs[6] = b1[2]; bs[7] = b1[3]; }
;         const bool head = (row0 & (SEQ - 1)) == 0;
;         const bf16_t* sp = src + (size_t)row0 * C + c0;
;         u32x4 x0, x1, x2;
;         if (head) { x0 = (u32x4){0u, 0u, 0u, 0u}; x1 = x0; x2 = x0; }
;         else { x0 = *(const u32x4*)(sp - (size_t)3 * C); x1 = *(const u32x4*)(sp - (size_t)2 * C); x2 = *(const u32x4*)(sp - (size_t)C); }
; #pragma unroll 4
;         for (int r = 0; r < 16; ++r) {
;             const u32x4 x3 = *(const u32x4*)(sp + (size_t)r * C);
;             const unsigned xa[4][4] = {{x0.x, x0.y, x0.z, x0.w}, {x1.x, x1.y, x1.z, x1.w}, {x2.x, x2.y, x2.z, x2.w}, {x3.x, x3.y, x3.z, x3.w}};
;             float a[8];
; #pragma unroll
;             for (int j = 0; j < 8; ++j) a[j] = bs[j];
; #pragma unroll
;             for (int k = 0; k < 4; ++k)
; #pragma unroll
;                 for (int q = 0; q < 4; ++q) { a[2 * q] += wt[k][2 * q] * bflo(xa[k][q]); a[2 * q + 1] += wt[k][2 * q + 1] * bfhi(xa[k][q]); }
;             if (SILU) {
; #pragma unroll
;                 for (int j = 0; j < 8; ++j) a[j] = fsilu(a[j]); }
;             u32x4 o; o.x = cvt_pk_bf16(a[0], a[1]); o.y = cvt_pk_bf16(a[2], a[3]); o.z = cvt_pk_bf16(a[4], a[5]); o.w = cvt_pk_bf16(a[6], a[7]);
;             *(u32x4*)(dst + (size_t)(row0 + r) * C + c0) = o;
;             x0 = x1; x1 = x2; x2 = x3;
;         }
.Lcv14_last3:
	s_waitcnt vmcnt(4)
	v_mov_b64_e32 v[36:37], v[106:107]
	v_mov_b64_e32 v[38:39], v[108:109]
.Lcv14_join3:
	v_lshlrev_b32_e32 v40, 16, v36
	v_pk_mul_f32 v[40:41], v[56:57], v[40:41]
	s_nop 0
	v_add_f32_e32 v1, v41, v1
	v_add_f32_e32 v1, v40, v1
	v_and_b32_e32 v40, 0xffff0000, v36
	v_mov_b32_e32 v41, v64
	v_pk_mul_f32 v[40:41], v[12:13], v[40:41]
	s_nop 0
	v_add_f32_e32 v41, v41, v42
	v_add_f32_e32 v42, v40, v41
	v_lshlrev_b32_e32 v40, 16, v37
	v_mov_b32_e32 v41, v66
	v_pk_mul_f32 v[40:41], v[44:45], v[40:41]
	s_nop 0
	v_add_f32_e32 v41, v41, v43
	v_add_f32_e32 v43, v40, v41
	v_and_b32_e32 v40, 0xffff0000, v37
	v_mov_b32_e32 v41, v68
	v_pk_mul_f32 v[40:41], v[14:15], v[40:41]
	s_nop 0
	v_add_f32_e32 v41, v41, v63
	v_add_f32_e32 v62, v40, v41
	v_lshlrev_b32_e32 v40, 16, v38
	v_mov_b32_e32 v41, v82
	v_pk_mul_f32 v[40:41], v[46:47], v[40:41]
	s_nop 0
	v_add_f32_e32 v41, v41, v65
	v_add_f32_e32 v63, v40, v41
	v_and_b32_e32 v40, 0xffff0000, v38
	v_mov_b32_e32 v41, v84
	v_pk_mul_f32 v[40:41], v[16:17], v[40:41]
	s_nop 0
	v_add_f32_e32 v41, v41, v67
	v_add_f32_e32 v64, v40, v41
	v_lshlrev_b32_e32 v40, 16, v39
	v_mov_b32_e32 v41, v86
	v_pk_mul_f32 v[40:41], v[2:3], v[40:41]
	s_nop 0
	v_add_f32_e32 v41, v41, v69
	v_add_f32_e32 v65, v40, v41
	v_and_b32_e32 v40, 0xffff0000, v39
	v_mov_b32_e32 v41, v90
	v_pk_mul_f32 v[40:41], v[18:19], v[40:41]
	s_nop 0
	v_add_f32_e32 v41, v41, v70
	v_add_f32_e32 v40, v40, v41
	v_mul_f32_e32 v41, 0xbfb8aa3b, v1
	v_exp_f32_e32 v41, v41
	s_nop 0
	v_add_f32_e32 v41, 1.0, v41
	v_rcp_f32_e32 v41, v41
	s_nop 0
	v_mul_f32_e32 v1, v1, v41
	v_mul_f32_e32 v41, 0xbfb8aa3b, v42
	v_exp_f32_e32 v41, v41
	s_nop 0
	v_add_f32_e32 v41, 1.0, v41
	v_rcp_f32_e32 v41, v41
	s_nop 0
	v_mul_f32_e32 v41, v42, v41
	v_mul_f32_e32 v42, 0xbfb8aa3b, v43
	v_exp_f32_e32 v42, v42
	s_nop 0
	v_add_f32_e32 v42, 1.0, v42
	v_rcp_f32_e32 v42, v42
	s_nop 0
	v_mul_f32_e32 v42, v43, v42
	v_mul_f32_e32 v43, 0xbfb8aa3b, v62
	v_exp_f32_e32 v43, v43
	s_nop 0
	v_add_f32_e32 v43, 1.0, v43
	v_rcp_f32_e32 v43, v43
	s_nop 0
	v_mul_f32_e32 v43, v62, v43
	v_mul_f32_e32 v62, 0xbfb8aa3b, v63
	v_exp_f32_e32 v62, v62
	s_nop 0
	v_add_f32_e32 v62, 1.0, v62
	v_rcp_f32_e32 v62, v62
	s_nop 0
	v_mul_f32_e32 v62, v63, v62
	v_mul_f32_e32 v63, 0xbfb8aa3b, v64
	v_exp_f32_e32 v63, v63
	s_nop 0
	v_add_f32_e32 v63, 1.0, v63
	v_rcp_f32_e32 v63, v63
	s_nop 0
	v_mul_f32_e32 v63, v64, v63
	v_mul_f32_e32 v64, 0xbfb8aa3b, v65
	v_exp_f32_e32 v64, v64
	s_nop 0
	v_add_f32_e32 v64, 1.0, v64
	v_rcp_f32_e32 v64, v64
	s_nop 0
	v_mul_f32_e32 v64, v65, v64
	v_mul_f32_e32 v65, 0xbfb8aa3b, v40
	v_exp_f32_e32 v65, v65
	s_nop 0
	v_add_f32_e32 v65, 1.0, v65
	v_rcp_f32_e32 v65, v65
	s_nop 0
	v_mul_f32_e32 v65, v40, v65
	v_cvt_pk_bf16_f32 v40, v1, v41
	v_cvt_pk_bf16_f32 v41, v42, v43
	v_cvt_pk_bf16_f32 v42, v62, v63
	v_cvt_pk_bf16_f32 v43, v64, v65
	global_store_dwordx4 v[60:61], v[40:43], off
	s_cbranch_scc0 .LBB0_154
	v_readlane_b32 s14, v254, 43
	v_readlane_b32 s15, v254, 44
	s_nop 0
	v_add_u32_e32 v88, s14, v88
	s_mov_b32 s14, 0x5ffff
	v_cmp_lt_i32_e32 vcc, s14, v88
	s_or_b64 s[12:13], vcc, s[12:13]
	s_andn2_b64 exec, exec, s[12:13]
	s_cbranch_execnz .LBB0_151

; __device__ __forceinline__ float bflo(unsigned w) { return __uint_as_float(w << 16); }
; __device__ __forceinline__ float bfhi(unsigned w) { return __uint_as_float(w & 0xffff0000u); }
; __device__ __forceinline__ void lru_scan_phase(const bf16_t* DD, const bf16_t* BB, const bf16_t* YG, bf16_t* Y, LAS float* sm, int tid, int bid, int G) {
;     ...
;     for (int w = bid; w < 256; w += G) {
;         const int b = w >> 6, ch = (w & 63) * 32 + cq * 4; const size_t base = ((size_t)b * SEQ + (size_t)sub * 32) * D + ch;
;         f32x4 P = (f32x4){1.f, 1.f, 1.f, 1.f}, Hh = (f32x4){0.f, 0.f, 0.f, 0.f};
; #pragma unroll 8
;         for (int t = 0; t < 32; ++t) { const u32x2 dw = *(const u32x2*)(DD + base + (size_t)t * D), bw = *(const u32x2*)(BB + base + (size_t)t * D);
;             const f32x4 a = (f32x4){1.f - bflo(dw.x), 1.f - bfhi(dw.x), 1.f - bflo(dw.y), 1.f - bfhi(dw.y)}, bv = (f32x4){bflo(bw.x), bfhi(bw.x), bflo(bw.y), bfhi(bw.y)}; Hh = a * Hh + bv; P = P * a; }
;         sP[tid] = P; sH[tid] = Hh;
.LBB0_469:
	s_and_b32 s0, s10, 7
	s_lshl_b32 s0, s0, 5
	s_lshr_b32 s1, s10, 3
	s_or_b32 s1, s0, s1
	s_lshl_b32 s0, s1, 5
	s_and_b32 s0, s0, 0x7e0
	v_or_b32_e32 v2, s0, v26
	s_ashr_i32 s0, s1, 6
	s_ashr_i32 s1, s0, 31
	s_lshl_b64 s[0:1], s[0:1], 22
	s_waitcnt lgkmcnt(0)
	v_mov_b32_e32 v3, v0
	v_lshl_add_u64 v[4:5], v[12:13], 0, s[0:1]
	v_lshl_add_u64 v[2:3], v[4:5], 0, v[2:3]
	v_lshl_add_u64 v[14:15], v[2:3], 1, s[38:39]
	v_mov_b32_e32 v2, 0
	v_mov_b32_e32 v6, 1.0
	s_mov_b64 s[0:1], 0
	v_mov_b32_e32 v7, v6
	v_mov_b32_e32 v8, v6
	v_mov_b32_e32 v9, v6
	v_mov_b32_e32 v3, v2
	v_mov_b32_e32 v4, v2
	v_mov_b32_e32 v5, v2
.LBB0_470:
	v_subrev_u32_e32 v242, s38, v14
	s_add_u32 s0, s38, 0x16c00000
	s_addc_u32 s1, s39, 0
	s_add_u32 s2, s38, 0x1ac00000
	s_addc_u32 s3, s39, 0
	v_add_u32_e32 v242, 0x1000, v242
	v_mov_b32_e32 v243, v242
	v_mov_b32_e32 v250, v242
	global_load_dwordx2 v[16:17], v242, s[0:1] offset:-4096
	global_load_dwordx2 v[82:83], v242, s[2:3] offset:-4096
	global_load_dwordx2 v[18:19], v242, s[0:1]
	global_load_dwordx2 v[84:85], v242, s[2:3]
	v_add_u32_e32 v242, 0x2000, v242
	global_load_dwordx2 v[20:21], v242, s[0:1] offset:-4096
	global_load_dwordx2 v[86:87], v242, s[2:3] offset:-4096
	global_load_dwordx2 v[22:23], v242, s[0:1]
	global_load_dwordx2 v[88:89], v242, s[2:3]
	v_add_u32_e32 v242, 0x2000, v242
	global_load_dwordx2 v[24:25], v242, s[0:1] offset:-4096
	global_load_dwordx2 v[90:91], v242, s[2:3] offset:-4096
	global_load_dwordx2 v[28:29], v242, s[0:1]
	global_load_dwordx2 v[92:93], v242, s[2:3]
	v_add_u32_e32 v242, 0x2000, v242
	global_load_dwordx2 v[30:31], v242, s[0:1] offset:-4096
	global_load_dwordx2 v[94:95], v242, s[2:3] offset:-4096
	global_load_dwordx2 v[32:33], v242, s[0:1]
	global_load_dwordx2 v[96:97], v242, s[2:3]
	v_add_u32_e32 v242, 0x2000, v242
	global_load_dwordx2 v[34:35], v242, s[0:1] offset:-4096
	global_load_dwordx2 v[98:99], v242, s[2:3] offset:-4096
	global_load_dwordx2 v[36:37], v242, s[0:1]
	global_load_dwordx2 v[100:101], v242, s[2:3]
	v_add_u32_e32 v242, 0x2000, v242
	global_load_dwordx2 v[38:39], v242, s[0:1] offset:-4096
	global_load_dwordx2 v[102:103], v242, s[2:3] offset:-4096
	global_load_dwordx2 v[40:41], v242, s[0:1]
	global_load_dwordx2 v[104:105], v242, s[2:3]
	v_add_u32_e32 v242, 0x2000, v242
	global_load_dwordx2 v[42:43], v242, s[0:1] offset:-4096
	global_load_dwordx2 v[106:107], v242, s[2:3] offset:-4096
	global_load_dwordx2 v[44:45], v242, s[0:1]
	global_load_dwordx2 v[108:109], v242, s[2:3]
	v_add_u32_e32 v242, 0x2000, v242
	global_load_dwordx2 v[46:47], v242, s[0:1] offset:-4096
	global_load_dwordx2 v[110:111], v242, s[2:3] offset:-4096
	global_load_dwordx2 v[48:49], v242, s[0:1]
	global_load_dwordx2 v[112:113], v242, s[2:3]
	v_add_u32_e32 v242, 0x2000, v242
	global_load_dwordx2 v[50:51], v242, s[0:1] offset:-4096
	global_load_dwordx2 v[114:115], v242, s[2:3] offset:-4096
	global_load_dwordx2 v[52:53], v242, s[0:1]
	global_load_dwordx2 v[116:117], v242, s[2:3]
	v_add_u32_e32 v242, 0x2000, v242
	global_load_dwordx2 v[54:55], v242, s[0:1] offset:-4096
	global_load_dwordx2 v[118:119], v242, s[2:3] offset:-4096
	global_load_dwordx2 v[56:57], v242, s[0:1]
	global_load_dwordx2 v[120:121], v242, s[2:3]
	v_add_u32_e32 v242, 0x2000, v242
	global_load_dwordx2 v[58:59], v242, s[0:1] offset:-4096
	global_load_dwordx2 v[122:123], v242, s[2:3] offset:-4096
	global_load_dwordx2 v[60:61], v242, s[0:1]
	global_load_dwordx2 v[124:125], v242, s[2:3]
	v_add_u32_e32 v242, 0x2000, v242
	global_load_dwordx2 v[62:63], v242, s[0:1] offset:-4096
	global_load_dwordx2 v[126:127], v242, s[2:3] offset:-4096
	global_load_dwordx2 v[64:65], v242, s[0:1]
	global_load_dwordx2 v[128:129], v242, s[2:3]
	v_add_u32_e32 v242, 0x2000, v242
	global_load_dwordx2 v[66:67], v242, s[0:1] offset:-4096
	global_load_dwordx2 v[130:131], v242, s[2:3] offset:-4096
	global_load_dwordx2 v[68:69], v242, s[0:1]
	global_load_dwordx2 v[132:133], v242, s[2:3]
	v_add_u32_e32 v242, 0x2000, v242
	global_load_dwordx2 v[70:71], v242, s[0:1] offset:-4096
	global_load_dwordx2 v[134:135], v242, s[2:3] offset:-4096
	global_load_dwordx2 v[72:73], v242, s[0:1]
	global_load_dwordx2 v[136:137], v242, s[2:3]
	v_add_u32_e32 v242, 0x2000, v242
	global_load_dwordx2 v[74:75], v242, s[0:1] offset:-4096
	global_load_dwordx2 v[138:139], v242, s[2:3] offset:-4096
	global_load_dwordx2 v[76:77], v242, s[0:1]
	global_load_dwordx2 v[140:141], v242, s[2:3]
	v_add_u32_e32 v242, 0x2000, v242
	s_waitcnt vmcnt(58)
	v_lshlrev_b32_e32 v234, 16, v16
	v_and_b32_e32 v235, 0xffff0000, v16
	v_lshlrev_b32_e32 v236, 16, v17
	v_and_b32_e32 v237, 0xffff0000, v17
	v_sub_f32_e32 v234, 1.0, v234
	v_sub_f32_e32 v235, 1.0, v235
	v_sub_f32_e32 v236, 1.0, v236
	v_sub_f32_e32 v237, 1.0, v237
	v_lshlrev_b32_e32 v238, 16, v82
	v_and_b32_e32 v239, 0xffff0000, v82
	v_lshlrev_b32_e32 v240, 16, v83
	v_and_b32_e32 v241, 0xffff0000, v83
	v_pk_fma_f32 v[2:3], v[2:3], v[234:235], v[238:239]
	v_pk_fma_f32 v[4:5], v[4:5], v[236:237], v[240:241]
	v_pk_mul_f32 v[6:7], v[6:7], v[234:235]
	v_pk_mul_f32 v[8:9], v[8:9], v[236:237]
	s_waitcnt vmcnt(56)
	v_lshlrev_b32_e32 v234, 16, v18
	v_and_b32_e32 v235, 0xffff0000, v18
	v_lshlrev_b32_e32 v236, 16, v19
	v_and_b32_e32 v237, 0xffff0000, v19
	v_sub_f32_e32 v234, 1.0, v234
	v_sub_f32_e32 v235, 1.0, v235
	v_sub_f32_e32 v236, 1.0, v236
	v_sub_f32_e32 v237, 1.0, v237
	v_lshlrev_b32_e32 v238, 16, v84
	v_and_b32_e32 v239, 0xffff0000, v84
	v_lshlrev_b32_e32 v240, 16, v85
	v_and_b32_e32 v241, 0xffff0000, v85
	v_pk_fma_f32 v[2:3], v[2:3], v[234:235], v[238:239]
	v_pk_fma_f32 v[4:5], v[4:5], v[236:237], v[240:241]
	v_pk_mul_f32 v[6:7], v[6:7], v[234:235]
	v_pk_mul_f32 v[8:9], v[8:9], v[236:237]
	global_load_dwordx2 v[78:79], v242, s[0:1] offset:-4096
	global_load_dwordx2 v[148:149], v242, s[2:3] offset:-4096
	global_load_dwordx2 v[80:81], v242, s[0:1]
	global_load_dwordx2 v[150:151], v242, s[2:3]
	s_add_u32 s0, s38, 0x12c00000
	s_addc_u32 s1, s39, 0
	s_nop 0
	global_load_dwordx2 v[156:157], v243, s[0:1] offset:-4096
	global_load_dwordx2 v[158:159], v243, s[0:1]
	v_add_u32_e32 v243, 0x2000, v243
	s_waitcnt vmcnt(60)
; __device__ __forceinline__ float bflo(unsigned w) { return __uint_as_float(w << 16); }
; __device__ __forceinline__ float bfhi(unsigned w) { return __uint_as_float(w & 0xffff0000u); }
; __device__ __forceinline__ void lru_scan_phase(const bf16_t* DD, const bf16_t* BB, const bf16_t* YG, bf16_t* Y, LAS float* sm, int tid, int bid, int G) {
;     ...
; #pragma unroll 8
;         for (int t = 0; t < 32; ++t) { const u32x2 dw = *(const u32x2*)(DD + base + (size_t)t * D), bw = *(const u32x2*)(BB + base + (size_t)t * D);
;             const f32x4 a = (f32x4){1.f - bflo(dw.x), 1.f - bfhi(dw.x), 1.f - bflo(dw.y), 1.f - bfhi(dw.y)}, bv = (f32x4){bflo(bw.x), bfhi(bw.x), bflo(bw.y), bfhi(bw.y)}; Hh = a * Hh + bv; P = P * a; }
	v_lshlrev_b32_e32 v234, 16, v20
	v_and_b32_e32 v235, 0xffff0000, v20
	v_lshlrev_b32_e32 v236, 16, v21
	v_and_b32_e32 v237, 0xffff0000, v21
	v_sub_f32_e32 v234, 1.0, v234
	v_sub_f32_e32 v235, 1.0, v235
	v_sub_f32_e32 v236, 1.0, v236
	v_sub_f32_e32 v237, 1.0, v237
	v_lshlrev_b32_e32 v238, 16, v86
	v_and_b32_e32 v239, 0xffff0000, v86
	v_lshlrev_b32_e32 v240, 16, v87
	v_and_b32_e32 v241, 0xffff0000, v87
	v_pk_fma_f32 v[2:3], v[2:3], v[234:235], v[238:239]
	v_pk_fma_f32 v[4:5], v[4:5], v[236:237], v[240:241]
	v_pk_mul_f32 v[6:7], v[6:7], v[234:235]
	v_pk_mul_f32 v[8:9], v[8:9], v[236:237]
	global_load_dwordx2 v[160:161], v243, s[0:1] offset:-4096
	s_waitcnt vmcnt(59)
	v_lshlrev_b32_e32 v234, 16, v22
	v_and_b32_e32 v235, 0xffff0000, v22
	v_lshlrev_b32_e32 v236, 16, v23
	v_and_b32_e32 v237, 0xffff0000, v23
	v_sub_f32_e32 v234, 1.0, v234
	v_sub_f32_e32 v235, 1.0, v235
	v_sub_f32_e32 v236, 1.0, v236
	v_sub_f32_e32 v237, 1.0, v237
	v_lshlrev_b32_e32 v238, 16, v88
	v_and_b32_e32 v239, 0xffff0000, v88
	v_lshlrev_b32_e32 v240, 16, v89
	v_and_b32_e32 v241, 0xffff0000, v89
	v_pk_fma_f32 v[2:3], v[2:3], v[234:235], v[238:239]
	v_pk_fma_f32 v[4:5], v[4:5], v[236:237], v[240:241]
	v_pk_mul_f32 v[6:7], v[6:7], v[234:235]
	v_pk_mul_f32 v[8:9], v[8:9], v[236:237]
	global_load_dwordx2 v[162:163], v243, s[0:1]
	v_add_u32_e32 v243, 0x2000, v243
	s_waitcnt vmcnt(58)
	v_lshlrev_b32_e32 v234, 16, v24
	v_and_b32_e32 v235, 0xffff0000, v24
	v_lshlrev_b32_e32 v236, 16, v25
	v_and_b32_e32 v237, 0xffff0000, v25
	v_sub_f32_e32 v234, 1.0, v234
	v_sub_f32_e32 v235, 1.0, v235
	v_sub_f32_e32 v236, 1.0, v236
	v_sub_f32_e32 v237, 1.0, v237
	v_lshlrev_b32_e32 v238, 16, v90
	v_and_b32_e32 v239, 0xffff0000, v90
	v_lshlrev_b32_e32 v240, 16, v91
	v_and_b32_e32 v241, 0xffff0000, v91
	v_pk_fma_f32 v[2:3], v[2:3], v[234:235], v[238:239]
	v_pk_fma_f32 v[4:5], v[4:5], v[236:237], v[240:241]
	v_pk_mul_f32 v[6:7], v[6:7], v[234:235]
	v_pk_mul_f32 v[8:9], v[8:9], v[236:237]
	global_load_dwordx2 v[164:165], v243, s[0:1] offset:-4096
	s_waitcnt vmcnt(57)
	v_lshlrev_b32_e32 v234, 16, v28
	v_and_b32_e32 v235, 0xffff0000, v28
	v_lshlrev_b32_e32 v236, 16, v29
	v_and_b32_e32 v237, 0xffff0000, v29
	v_sub_f32_e32 v234, 1.0, v234
	v_sub_f32_e32 v235, 1.0, v235
	v_sub_f32_e32 v236, 1.0, v236
	v_sub_f32_e32 v237, 1.0, v237
	v_lshlrev_b32_e32 v238, 16, v92
	v_and_b32_e32 v239, 0xffff0000, v92
	v_lshlrev_b32_e32 v240, 16, v93
	v_and_b32_e32 v241, 0xffff0000, v93
	v_pk_fma_f32 v[2:3], v[2:3], v[234:235], v[238:239]
	v_pk_fma_f32 v[4:5], v[4:5], v[236:237], v[240:241]
	v_pk_mul_f32 v[6:7], v[6:7], v[234:235]
	v_pk_mul_f32 v[8:9], v[8:9], v[236:237]
	global_load_dwordx2 v[166:167], v243, s[0:1]
	v_add_u32_e32 v243, 0x2000, v243
	s_waitcnt vmcnt(56)
	v_lshlrev_b32_e32 v234, 16, v30
	v_and_b32_e32 v235, 0xffff0000, v30
	v_lshlrev_b32_e32 v236, 16, v31
	v_and_b32_e32 v237, 0xffff0000, v31
	v_sub_f32_e32 v234, 1.0, v234
	v_sub_f32_e32 v235, 1.0, v235
	v_sub_f32_e32 v236, 1.0, v236
	v_sub_f32_e32 v237, 1.0, v237
	v_lshlrev_b32_e32 v238, 16, v94
	v_and_b32_e32 v239, 0xffff0000, v94
	v_lshlrev_b32_e32 v240, 16, v95
	v_and_b32_e32 v241, 0xffff0000, v95
	v_pk_fma_f32 v[2:3], v[2:3], v[234:235], v[238:239]
	v_pk_fma_f32 v[4:5], v[4:5], v[236:237], v[240:241]
	v_pk_mul_f32 v[6:7], v[6:7], v[234:235]
	v_pk_mul_f32 v[8:9], v[8:9], v[236:237]
	global_load_dwordx2 v[168:169], v243, s[0:1] offset:-4096
	s_waitcnt vmcnt(55)
	v_lshlrev_b32_e32 v234, 16, v32
	v_and_b32_e32 v235, 0xffff0000, v32
	v_lshlrev_b32_e32 v236, 16, v33
	v_and_b32_e32 v237, 0xffff0000, v33
	v_sub_f32_e32 v234, 1.0, v234
	v_sub_f32_e32 v235, 1.0, v235
	v_sub_f32_e32 v236, 1.0, v236
	v_sub_f32_e32 v237, 1.0, v237
	v_lshlrev_b32_e32 v238, 16, v96
	v_and_b32_e32 v239, 0xffff0000, v96
	v_lshlrev_b32_e32 v240, 16, v97
	v_and_b32_e32 v241, 0xffff0000, v97
	v_pk_fma_f32 v[2:3], v[2:3], v[234:235], v[238:239]
	v_pk_fma_f32 v[4:5], v[4:5], v[236:237], v[240:241]
	v_pk_mul_f32 v[6:7], v[6:7], v[234:235]
	v_pk_mul_f32 v[8:9], v[8:9], v[236:237]
	global_load_dwordx2 v[170:171], v243, s[0:1]
	v_add_u32_e32 v243, 0x2000, v243
	s_waitcnt vmcnt(54)
	v_lshlrev_b32_e32 v234, 16, v34
	v_and_b32_e32 v235, 0xffff0000, v34
	v_lshlrev_b32_e32 v236, 16, v35
	v_and_b32_e32 v237, 0xffff0000, v35
	v_sub_f32_e32 v234, 1.0, v234
	v_sub_f32_e32 v235, 1.0, v235
	v_sub_f32_e32 v236, 1.0, v236
	v_sub_f32_e32 v237, 1.0, v237
	v_lshlrev_b32_e32 v238, 16, v98
	v_and_b32_e32 v239, 0xffff0000, v98
	v_lshlrev_b32_e32 v240, 16, v99
	v_and_b32_e32 v241, 0xffff0000, v99
	v_pk_fma_f32 v[2:3], v[2:3], v[234:235], v[238:239]
	v_pk_fma_f32 v[4:5], v[4:5], v[236:237], v[240:241]
	v_pk_mul_f32 v[6:7], v[6:7], v[234:235]
	v_pk_mul_f32 v[8:9], v[8:9], v[236:237]
	global_load_dwordx2 v[172:173], v243, s[0:1] offset:-4096
	s_waitcnt vmcnt(53)
	v_lshlrev_b32_e32 v234, 16, v36
	v_and_b32_e32 v235, 0xffff0000, v36
	v_lshlrev_b32_e32 v236, 16, v37
	v_and_b32_e32 v237, 0xffff0000, v37
	v_sub_f32_e32 v234, 1.0, v234
	v_sub_f32_e32 v235, 1.0, v235
	v_sub_f32_e32 v236, 1.0, v236
	v_sub_f32_e32 v237, 1.0, v237
	v_lshlrev_b32_e32 v238, 16, v100
	v_and_b32_e32 v239, 0xffff0000, v100
	v_lshlrev_b32_e32 v240, 16, v101
	v_and_b32_e32 v241, 0xffff0000, v101
	v_pk_fma_f32 v[2:3], v[2:3], v[234:235], v[238:239]
	v_pk_fma_f32 v[4:5], v[4:5], v[236:237], v[240:241]
	v_pk_mul_f32 v[6:7], v[6:7], v[234:235]
	v_pk_mul_f32 v[8:9], v[8:9], v[236:237]
	global_load_dwordx2 v[174:175], v243, s[0:1]
	v_add_u32_e32 v243, 0x2000, v243
	s_waitcnt vmcnt(52)
; __device__ __forceinline__ float bflo(unsigned w) { return __uint_as_float(w << 16); }
; __device__ __forceinline__ float bfhi(unsigned w) { return __uint_as_float(w & 0xffff0000u); }
; __device__ __forceinline__ void lru_scan_phase(const bf16_t* DD, const bf16_t* BB, const bf16_t* YG, bf16_t* Y, LAS float* sm, int tid, int bid, int G) {
;     ...
; #pragma unroll 8
;         for (int t = 0; t < 32; ++t) { const u32x2 dw = *(const u32x2*)(DD + base + (size_t)t * D), bw = *(const u32x2*)(BB + base + (size_t)t * D);
;             const f32x4 a = (f32x4){1.f - bflo(dw.x), 1.f - bfhi(dw.x), 1.f - bflo(dw.y), 1.f - bfhi(dw.y)}, bv = (f32x4){bflo(bw.x), bfhi(bw.x), bflo(bw.y), bfhi(bw.y)}; Hh = a * Hh + bv; P = P * a; }
	v_lshlrev_b32_e32 v234, 16, v38
	v_and_b32_e32 v235, 0xffff0000, v38
	v_lshlrev_b32_e32 v236, 16, v39
	v_and_b32_e32 v237, 0xffff0000, v39
	v_sub_f32_e32 v234, 1.0, v234
	v_sub_f32_e32 v235, 1.0, v235
	v_sub_f32_e32 v236, 1.0, v236
	v_sub_f32_e32 v237, 1.0, v237
	v_lshlrev_b32_e32 v238, 16, v102
	v_and_b32_e32 v239, 0xffff0000, v102
	v_lshlrev_b32_e32 v240, 16, v103
	v_and_b32_e32 v241, 0xffff0000, v103
	v_pk_fma_f32 v[2:3], v[2:3], v[234:235], v[238:239]
	v_pk_fma_f32 v[4:5], v[4:5], v[236:237], v[240:241]
	v_pk_mul_f32 v[6:7], v[6:7], v[234:235]
	v_pk_mul_f32 v[8:9], v[8:9], v[236:237]
	global_load_dwordx2 v[176:177], v243, s[0:1] offset:-4096
	s_waitcnt vmcnt(51)
	v_lshlrev_b32_e32 v234, 16, v40
	v_and_b32_e32 v235, 0xffff0000, v40
	v_lshlrev_b32_e32 v236, 16, v41
	v_and_b32_e32 v237, 0xffff0000, v41
	v_sub_f32_e32 v234, 1.0, v234
	v_sub_f32_e32 v235, 1.0, v235
	v_sub_f32_e32 v236, 1.0, v236
	v_sub_f32_e32 v237, 1.0, v237
	v_lshlrev_b32_e32 v238, 16, v104
	v_and_b32_e32 v239, 0xffff0000, v104
	v_lshlrev_b32_e32 v240, 16, v105
	v_and_b32_e32 v241, 0xffff0000, v105
	v_pk_fma_f32 v[2:3], v[2:3], v[234:235], v[238:239]
	v_pk_fma_f32 v[4:5], v[4:5], v[236:237], v[240:241]
	v_pk_mul_f32 v[6:7], v[6:7], v[234:235]
	v_pk_mul_f32 v[8:9], v[8:9], v[236:237]
	global_load_dwordx2 v[178:179], v243, s[0:1]
	v_add_u32_e32 v243, 0x2000, v243
	s_waitcnt vmcnt(50)
	v_lshlrev_b32_e32 v234, 16, v42
	v_and_b32_e32 v235, 0xffff0000, v42
	v_lshlrev_b32_e32 v236, 16, v43
	v_and_b32_e32 v237, 0xffff0000, v43
	v_sub_f32_e32 v234, 1.0, v234
	v_sub_f32_e32 v235, 1.0, v235
	v_sub_f32_e32 v236, 1.0, v236
	v_sub_f32_e32 v237, 1.0, v237
	v_lshlrev_b32_e32 v238, 16, v106
	v_and_b32_e32 v239, 0xffff0000, v106
	v_lshlrev_b32_e32 v240, 16, v107
	v_and_b32_e32 v241, 0xffff0000, v107
	v_pk_fma_f32 v[2:3], v[2:3], v[234:235], v[238:239]
	v_pk_fma_f32 v[4:5], v[4:5], v[236:237], v[240:241]
	v_pk_mul_f32 v[6:7], v[6:7], v[234:235]
	v_pk_mul_f32 v[8:9], v[8:9], v[236:237]
	global_load_dwordx2 v[180:181], v243, s[0:1] offset:-4096
	s_waitcnt vmcnt(49)
	v_lshlrev_b32_e32 v234, 16, v44
	v_and_b32_e32 v235, 0xffff0000, v44
	v_lshlrev_b32_e32 v236, 16, v45
	v_and_b32_e32 v237, 0xffff0000, v45
	v_sub_f32_e32 v234, 1.0, v234
	v_sub_f32_e32 v235, 1.0, v235
	v_sub_f32_e32 v236, 1.0, v236
	v_sub_f32_e32 v237, 1.0, v237
	v_lshlrev_b32_e32 v238, 16, v108
	v_and_b32_e32 v239, 0xffff0000, v108
	v_lshlrev_b32_e32 v240, 16, v109
	v_and_b32_e32 v241, 0xffff0000, v109
	v_pk_fma_f32 v[2:3], v[2:3], v[234:235], v[238:239]
	v_pk_fma_f32 v[4:5], v[4:5], v[236:237], v[240:241]
	v_pk_mul_f32 v[6:7], v[6:7], v[234:235]
	v_pk_mul_f32 v[8:9], v[8:9], v[236:237]
	global_load_dwordx2 v[182:183], v243, s[0:1]
	v_add_u32_e32 v243, 0x2000, v243
	s_waitcnt vmcnt(48)
	v_lshlrev_b32_e32 v234, 16, v46
	v_and_b32_e32 v235, 0xffff0000, v46
	v_lshlrev_b32_e32 v236, 16, v47
	v_and_b32_e32 v237, 0xffff0000, v47
	v_sub_f32_e32 v234, 1.0, v234
	v_sub_f32_e32 v235, 1.0, v235
	v_sub_f32_e32 v236, 1.0, v236
	v_sub_f32_e32 v237, 1.0, v237
	v_lshlrev_b32_e32 v238, 16, v110
	v_and_b32_e32 v239, 0xffff0000, v110
	v_lshlrev_b32_e32 v240, 16, v111
	v_and_b32_e32 v241, 0xffff0000, v111
	v_pk_fma_f32 v[2:3], v[2:3], v[234:235], v[238:239]
	v_pk_fma_f32 v[4:5], v[4:5], v[236:237], v[240:241]
	v_pk_mul_f32 v[6:7], v[6:7], v[234:235]
	v_pk_mul_f32 v[8:9], v[8:9], v[236:237]
	global_load_dwordx2 v[184:185], v243, s[0:1] offset:-4096
	s_waitcnt vmcnt(47)
	v_lshlrev_b32_e32 v234, 16, v48
	v_and_b32_e32 v235, 0xffff0000, v48
	v_lshlrev_b32_e32 v236, 16, v49
	v_and_b32_e32 v237, 0xffff0000, v49
	v_sub_f32_e32 v234, 1.0, v234
	v_sub_f32_e32 v235, 1.0, v235
	v_sub_f32_e32 v236, 1.0, v236
	v_sub_f32_e32 v237, 1.0, v237
	v_lshlrev_b32_e32 v238, 16, v112
	v_and_b32_e32 v239, 0xffff0000, v112
	v_lshlrev_b32_e32 v240, 16, v113
	v_and_b32_e32 v241, 0xffff0000, v113
	v_pk_fma_f32 v[2:3], v[2:3], v[234:235], v[238:239]
	v_pk_fma_f32 v[4:5], v[4:5], v[236:237], v[240:241]
	v_pk_mul_f32 v[6:7], v[6:7], v[234:235]
	v_pk_mul_f32 v[8:9], v[8:9], v[236:237]
	global_load_dwordx2 v[186:187], v243, s[0:1]
	v_add_u32_e32 v243, 0x2000, v243
	s_waitcnt vmcnt(46)
	v_lshlrev_b32_e32 v234, 16, v50
	v_and_b32_e32 v235, 0xffff0000, v50
	v_lshlrev_b32_e32 v236, 16, v51
	v_and_b32_e32 v237, 0xffff0000, v51
	v_sub_f32_e32 v234, 1.0, v234
	v_sub_f32_e32 v235, 1.0, v235
	v_sub_f32_e32 v236, 1.0, v236
	v_sub_f32_e32 v237, 1.0, v237
	v_lshlrev_b32_e32 v238, 16, v114
	v_and_b32_e32 v239, 0xffff0000, v114
	v_lshlrev_b32_e32 v240, 16, v115
	v_and_b32_e32 v241, 0xffff0000, v115
	v_pk_fma_f32 v[2:3], v[2:3], v[234:235], v[238:239]
	v_pk_fma_f32 v[4:5], v[4:5], v[236:237], v[240:241]
	v_pk_mul_f32 v[6:7], v[6:7], v[234:235]
	v_pk_mul_f32 v[8:9], v[8:9], v[236:237]
	global_load_dwordx2 v[188:189], v243, s[0:1] offset:-4096
	s_waitcnt vmcnt(45)
	v_lshlrev_b32_e32 v234, 16, v52
	v_and_b32_e32 v235, 0xffff0000, v52
	v_lshlrev_b32_e32 v236, 16, v53
	v_and_b32_e32 v237, 0xffff0000, v53
	v_sub_f32_e32 v234, 1.0, v234
	v_sub_f32_e32 v235, 1.0, v235
	v_sub_f32_e32 v236, 1.0, v236
	v_sub_f32_e32 v237, 1.0, v237
	v_lshlrev_b32_e32 v238, 16, v116
	v_and_b32_e32 v239, 0xffff0000, v116
	v_lshlrev_b32_e32 v240, 16, v117
	v_and_b32_e32 v241, 0xffff0000, v117
	v_pk_fma_f32 v[2:3], v[2:3], v[234:235], v[238:239]
	v_pk_fma_f32 v[4:5], v[4:5], v[236:237], v[240:241]
	v_pk_mul_f32 v[6:7], v[6:7], v[234:235]
	v_pk_mul_f32 v[8:9], v[8:9], v[236:237]
	global_load_dwordx2 v[190:191], v243, s[0:1]
	v_add_u32_e32 v243, 0x2000, v243
	s_waitcnt vmcnt(44)
; __device__ __forceinline__ float bflo(unsigned w) { return __uint_as_float(w << 16); }
; __device__ __forceinline__ float bfhi(unsigned w) { return __uint_as_float(w & 0xffff0000u); }
; __device__ __forceinline__ void lru_scan_phase(const bf16_t* DD, const bf16_t* BB, const bf16_t* YG, bf16_t* Y, LAS float* sm, int tid, int bid, int G) {
;     ...
; #pragma unroll 8
;         for (int t = 0; t < 32; ++t) { const u32x2 dw = *(const u32x2*)(DD + base + (size_t)t * D), bw = *(const u32x2*)(BB + base + (size_t)t * D);
;             const f32x4 a = (f32x4){1.f - bflo(dw.x), 1.f - bfhi(dw.x), 1.f - bflo(dw.y), 1.f - bfhi(dw.y)}, bv = (f32x4){bflo(bw.x), bfhi(bw.x), bflo(bw.y), bfhi(bw.y)}; Hh = a * Hh + bv; P = P * a; }
	v_lshlrev_b32_e32 v234, 16, v54
	v_and_b32_e32 v235, 0xffff0000, v54
	v_lshlrev_b32_e32 v236, 16, v55
	v_and_b32_e32 v237, 0xffff0000, v55
	v_sub_f32_e32 v234, 1.0, v234
	v_sub_f32_e32 v235, 1.0, v235
	v_sub_f32_e32 v236, 1.0, v236
	v_sub_f32_e32 v237, 1.0, v237
	v_lshlrev_b32_e32 v238, 16, v118
	v_and_b32_e32 v239, 0xffff0000, v118
	v_lshlrev_b32_e32 v240, 16, v119
	v_and_b32_e32 v241, 0xffff0000, v119
	v_pk_fma_f32 v[2:3], v[2:3], v[234:235], v[238:239]
	v_pk_fma_f32 v[4:5], v[4:5], v[236:237], v[240:241]
	v_pk_mul_f32 v[6:7], v[6:7], v[234:235]
	v_pk_mul_f32 v[8:9], v[8:9], v[236:237]
	global_load_dwordx2 v[192:193], v243, s[0:1] offset:-4096
	s_waitcnt vmcnt(43)
	v_lshlrev_b32_e32 v234, 16, v56
	v_and_b32_e32 v235, 0xffff0000, v56
	v_lshlrev_b32_e32 v236, 16, v57
	v_and_b32_e32 v237, 0xffff0000, v57
	v_sub_f32_e32 v234, 1.0, v234
	v_sub_f32_e32 v235, 1.0, v235
	v_sub_f32_e32 v236, 1.0, v236
	v_sub_f32_e32 v237, 1.0, v237
	v_lshlrev_b32_e32 v238, 16, v120
	v_and_b32_e32 v239, 0xffff0000, v120
	v_lshlrev_b32_e32 v240, 16, v121
	v_and_b32_e32 v241, 0xffff0000, v121
	v_pk_fma_f32 v[2:3], v[2:3], v[234:235], v[238:239]
	v_pk_fma_f32 v[4:5], v[4:5], v[236:237], v[240:241]
	v_pk_mul_f32 v[6:7], v[6:7], v[234:235]
	v_pk_mul_f32 v[8:9], v[8:9], v[236:237]
	global_load_dwordx2 v[194:195], v243, s[0:1]
	v_add_u32_e32 v243, 0x2000, v243
	s_waitcnt vmcnt(42)
	v_lshlrev_b32_e32 v234, 16, v58
	v_and_b32_e32 v235, 0xffff0000, v58
	v_lshlrev_b32_e32 v236, 16, v59
	v_and_b32_e32 v237, 0xffff0000, v59
	v_sub_f32_e32 v234, 1.0, v234
	v_sub_f32_e32 v235, 1.0, v235
	v_sub_f32_e32 v236, 1.0, v236
	v_sub_f32_e32 v237, 1.0, v237
	v_lshlrev_b32_e32 v238, 16, v122
	v_and_b32_e32 v239, 0xffff0000, v122
	v_lshlrev_b32_e32 v240, 16, v123
	v_and_b32_e32 v241, 0xffff0000, v123
	v_pk_fma_f32 v[2:3], v[2:3], v[234:235], v[238:239]
	v_pk_fma_f32 v[4:5], v[4:5], v[236:237], v[240:241]
	v_pk_mul_f32 v[6:7], v[6:7], v[234:235]
	v_pk_mul_f32 v[8:9], v[8:9], v[236:237]
	global_load_dwordx2 v[198:199], v243, s[0:1] offset:-4096
	s_waitcnt vmcnt(41)
	v_lshlrev_b32_e32 v234, 16, v60
	v_and_b32_e32 v235, 0xffff0000, v60
	v_lshlrev_b32_e32 v236, 16, v61
	v_and_b32_e32 v237, 0xffff0000, v61
	v_sub_f32_e32 v234, 1.0, v234
	v_sub_f32_e32 v235, 1.0, v235
	v_sub_f32_e32 v236, 1.0, v236
	v_sub_f32_e32 v237, 1.0, v237
	v_lshlrev_b32_e32 v238, 16, v124
	v_and_b32_e32 v239, 0xffff0000, v124
	v_lshlrev_b32_e32 v240, 16, v125
	v_and_b32_e32 v241, 0xffff0000, v125
	v_pk_fma_f32 v[2:3], v[2:3], v[234:235], v[238:239]
	v_pk_fma_f32 v[4:5], v[4:5], v[236:237], v[240:241]
	v_pk_mul_f32 v[6:7], v[6:7], v[234:235]
	v_pk_mul_f32 v[8:9], v[8:9], v[236:237]
	global_load_dwordx2 v[204:205], v243, s[0:1]
	v_add_u32_e32 v243, 0x2000, v243
	s_waitcnt vmcnt(40)
	v_lshlrev_b32_e32 v234, 16, v62
	v_and_b32_e32 v235, 0xffff0000, v62
	v_lshlrev_b32_e32 v236, 16, v63
	v_and_b32_e32 v237, 0xffff0000, v63
	v_sub_f32_e32 v234, 1.0, v234
	v_sub_f32_e32 v235, 1.0, v235
	v_sub_f32_e32 v236, 1.0, v236
	v_sub_f32_e32 v237, 1.0, v237
	v_lshlrev_b32_e32 v238, 16, v126
	v_and_b32_e32 v239, 0xffff0000, v126
	v_lshlrev_b32_e32 v240, 16, v127
	v_and_b32_e32 v241, 0xffff0000, v127
	v_pk_fma_f32 v[2:3], v[2:3], v[234:235], v[238:239]
	v_pk_fma_f32 v[4:5], v[4:5], v[236:237], v[240:241]
	v_pk_mul_f32 v[6:7], v[6:7], v[234:235]
	v_pk_mul_f32 v[8:9], v[8:9], v[236:237]
	global_load_dwordx2 v[214:215], v243, s[0:1] offset:-4096
	s_waitcnt vmcnt(39)
	v_lshlrev_b32_e32 v234, 16, v64
	v_and_b32_e32 v235, 0xffff0000, v64
	v_lshlrev_b32_e32 v236, 16, v65
	v_and_b32_e32 v237, 0xffff0000, v65
	v_sub_f32_e32 v234, 1.0, v234
	v_sub_f32_e32 v235, 1.0, v235
	v_sub_f32_e32 v236, 1.0, v236
	v_sub_f32_e32 v237, 1.0, v237
	v_lshlrev_b32_e32 v238, 16, v128
	v_and_b32_e32 v239, 0xffff0000, v128
	v_lshlrev_b32_e32 v240, 16, v129
	v_and_b32_e32 v241, 0xffff0000, v129
	v_pk_fma_f32 v[2:3], v[2:3], v[234:235], v[238:239]
	v_pk_fma_f32 v[4:5], v[4:5], v[236:237], v[240:241]
	v_pk_mul_f32 v[6:7], v[6:7], v[234:235]
	v_pk_mul_f32 v[8:9], v[8:9], v[236:237]
	global_load_dwordx2 v[216:217], v243, s[0:1]
	v_add_u32_e32 v243, 0x2000, v243
	s_waitcnt vmcnt(38)
	v_lshlrev_b32_e32 v234, 16, v66
	v_and_b32_e32 v235, 0xffff0000, v66
	v_lshlrev_b32_e32 v236, 16, v67
	v_and_b32_e32 v237, 0xffff0000, v67
	v_sub_f32_e32 v234, 1.0, v234
	v_sub_f32_e32 v235, 1.0, v235
	v_sub_f32_e32 v236, 1.0, v236
	v_sub_f32_e32 v237, 1.0, v237
	v_lshlrev_b32_e32 v238, 16, v130
	v_and_b32_e32 v239, 0xffff0000, v130
	v_lshlrev_b32_e32 v240, 16, v131
	v_and_b32_e32 v241, 0xffff0000, v131
	v_pk_fma_f32 v[2:3], v[2:3], v[234:235], v[238:239]
	v_pk_fma_f32 v[4:5], v[4:5], v[236:237], v[240:241]
	v_pk_mul_f32 v[6:7], v[6:7], v[234:235]
	v_pk_mul_f32 v[8:9], v[8:9], v[236:237]
	global_load_dwordx2 v[218:219], v243, s[0:1] offset:-4096
	s_waitcnt vmcnt(37)
	v_lshlrev_b32_e32 v234, 16, v68
	v_and_b32_e32 v235, 0xffff0000, v68
	v_lshlrev_b32_e32 v236, 16, v69
	v_and_b32_e32 v237, 0xffff0000, v69
	v_sub_f32_e32 v234, 1.0, v234
	v_sub_f32_e32 v235, 1.0, v235
	v_sub_f32_e32 v236, 1.0, v236
	v_sub_f32_e32 v237, 1.0, v237
	v_lshlrev_b32_e32 v238, 16, v132
	v_and_b32_e32 v239, 0xffff0000, v132
	v_lshlrev_b32_e32 v240, 16, v133
	v_and_b32_e32 v241, 0xffff0000, v133
	v_pk_fma_f32 v[2:3], v[2:3], v[234:235], v[238:239]
	v_pk_fma_f32 v[4:5], v[4:5], v[236:237], v[240:241]
	v_pk_mul_f32 v[6:7], v[6:7], v[234:235]
	v_pk_mul_f32 v[8:9], v[8:9], v[236:237]
	global_load_dwordx2 v[220:221], v243, s[0:1]
	v_add_u32_e32 v243, 0x2000, v243
	s_waitcnt vmcnt(36)
; __device__ __forceinline__ float bflo(unsigned w) { return __uint_as_float(w << 16); }
; __device__ __forceinline__ float bfhi(unsigned w) { return __uint_as_float(w & 0xffff0000u); }
; __device__ __forceinline__ void lru_scan_phase(const bf16_t* DD, const bf16_t* BB, const bf16_t* YG, bf16_t* Y, LAS float* sm, int tid, int bid, int G) {
;     ...
; #pragma unroll 8
;         for (int t = 0; t < 32; ++t) { const u32x2 dw = *(const u32x2*)(DD + base + (size_t)t * D), bw = *(const u32x2*)(BB + base + (size_t)t * D);
;             const f32x4 a = (f32x4){1.f - bflo(dw.x), 1.f - bfhi(dw.x), 1.f - bflo(dw.y), 1.f - bfhi(dw.y)}, bv = (f32x4){bflo(bw.x), bfhi(bw.x), bflo(bw.y), bfhi(bw.y)}; Hh = a * Hh + bv; P = P * a; }
;         sP[tid] = P; sH[tid] = Hh;
;         __syncthreads();
;         f32x4 h = (f32x4){0.f, 0.f, 0.f, 0.f};
;         for (int k = 0; k < sub; ++k) h = sP[k * 8 + cq] * h + sH[k * 8 + cq];
	v_lshlrev_b32_e32 v234, 16, v70
	v_and_b32_e32 v235, 0xffff0000, v70
	v_lshlrev_b32_e32 v236, 16, v71
	v_and_b32_e32 v237, 0xffff0000, v71
	v_sub_f32_e32 v234, 1.0, v234
	v_sub_f32_e32 v235, 1.0, v235
	v_sub_f32_e32 v236, 1.0, v236
	v_sub_f32_e32 v237, 1.0, v237
	v_lshlrev_b32_e32 v238, 16, v134
	v_and_b32_e32 v239, 0xffff0000, v134
	v_lshlrev_b32_e32 v240, 16, v135
	v_and_b32_e32 v241, 0xffff0000, v135
	v_pk_fma_f32 v[2:3], v[2:3], v[234:235], v[238:239]
	v_pk_fma_f32 v[4:5], v[4:5], v[236:237], v[240:241]
	v_pk_mul_f32 v[6:7], v[6:7], v[234:235]
	v_pk_mul_f32 v[8:9], v[8:9], v[236:237]
	global_load_dwordx2 v[222:223], v243, s[0:1] offset:-4096
	s_waitcnt vmcnt(35)
	v_lshlrev_b32_e32 v234, 16, v72
	v_and_b32_e32 v235, 0xffff0000, v72
	v_lshlrev_b32_e32 v236, 16, v73
	v_and_b32_e32 v237, 0xffff0000, v73
	v_sub_f32_e32 v234, 1.0, v234
	v_sub_f32_e32 v235, 1.0, v235
	v_sub_f32_e32 v236, 1.0, v236
	v_sub_f32_e32 v237, 1.0, v237
	v_lshlrev_b32_e32 v238, 16, v136
	v_and_b32_e32 v239, 0xffff0000, v136
	v_lshlrev_b32_e32 v240, 16, v137
	v_and_b32_e32 v241, 0xffff0000, v137
	v_pk_fma_f32 v[2:3], v[2:3], v[234:235], v[238:239]
	v_pk_fma_f32 v[4:5], v[4:5], v[236:237], v[240:241]
	v_pk_mul_f32 v[6:7], v[6:7], v[234:235]
	v_pk_mul_f32 v[8:9], v[8:9], v[236:237]
	global_load_dwordx2 v[224:225], v243, s[0:1]
	v_add_u32_e32 v243, 0x2000, v243
	s_waitcnt vmcnt(34)
	v_lshlrev_b32_e32 v234, 16, v74
	v_and_b32_e32 v235, 0xffff0000, v74
	v_lshlrev_b32_e32 v236, 16, v75
	v_and_b32_e32 v237, 0xffff0000, v75
	v_sub_f32_e32 v234, 1.0, v234
	v_sub_f32_e32 v235, 1.0, v235
	v_sub_f32_e32 v236, 1.0, v236
	v_sub_f32_e32 v237, 1.0, v237
	v_lshlrev_b32_e32 v238, 16, v138
	v_and_b32_e32 v239, 0xffff0000, v138
	v_lshlrev_b32_e32 v240, 16, v139
	v_and_b32_e32 v241, 0xffff0000, v139
	v_pk_fma_f32 v[2:3], v[2:3], v[234:235], v[238:239]
	v_pk_fma_f32 v[4:5], v[4:5], v[236:237], v[240:241]
	v_pk_mul_f32 v[6:7], v[6:7], v[234:235]
	v_pk_mul_f32 v[8:9], v[8:9], v[236:237]
	global_load_dwordx2 v[226:227], v243, s[0:1] offset:-4096
	s_waitcnt vmcnt(33)
	v_lshlrev_b32_e32 v234, 16, v76
	v_and_b32_e32 v235, 0xffff0000, v76
	v_lshlrev_b32_e32 v236, 16, v77
	v_and_b32_e32 v237, 0xffff0000, v77
	v_sub_f32_e32 v234, 1.0, v234
	v_sub_f32_e32 v235, 1.0, v235
	v_sub_f32_e32 v236, 1.0, v236
	v_sub_f32_e32 v237, 1.0, v237
	v_lshlrev_b32_e32 v238, 16, v140
	v_and_b32_e32 v239, 0xffff0000, v140
	v_lshlrev_b32_e32 v240, 16, v141
	v_and_b32_e32 v241, 0xffff0000, v141
	v_pk_fma_f32 v[2:3], v[2:3], v[234:235], v[238:239]
	v_pk_fma_f32 v[4:5], v[4:5], v[236:237], v[240:241]
	v_pk_mul_f32 v[6:7], v[6:7], v[234:235]
	v_pk_mul_f32 v[8:9], v[8:9], v[236:237]
	global_load_dwordx2 v[228:229], v243, s[0:1]
	v_add_u32_e32 v243, 0x2000, v243
	s_waitcnt vmcnt(32)
	v_lshlrev_b32_e32 v234, 16, v78
	v_and_b32_e32 v235, 0xffff0000, v78
	v_lshlrev_b32_e32 v236, 16, v79
	v_and_b32_e32 v237, 0xffff0000, v79
	v_sub_f32_e32 v234, 1.0, v234
	v_sub_f32_e32 v235, 1.0, v235
	v_sub_f32_e32 v236, 1.0, v236
	v_sub_f32_e32 v237, 1.0, v237
	v_lshlrev_b32_e32 v238, 16, v148
	v_and_b32_e32 v239, 0xffff0000, v148
	v_lshlrev_b32_e32 v240, 16, v149
	v_and_b32_e32 v241, 0xffff0000, v149
	v_pk_fma_f32 v[2:3], v[2:3], v[234:235], v[238:239]
	v_pk_fma_f32 v[4:5], v[4:5], v[236:237], v[240:241]
	v_pk_mul_f32 v[6:7], v[6:7], v[234:235]
	v_pk_mul_f32 v[8:9], v[8:9], v[236:237]
	global_load_dwordx2 v[230:231], v243, s[0:1] offset:-4096
	s_waitcnt vmcnt(31)
	v_lshlrev_b32_e32 v234, 16, v80
	v_and_b32_e32 v235, 0xffff0000, v80
	v_lshlrev_b32_e32 v236, 16, v81
	v_and_b32_e32 v237, 0xffff0000, v81
	v_sub_f32_e32 v234, 1.0, v234
	v_sub_f32_e32 v235, 1.0, v235
	v_sub_f32_e32 v236, 1.0, v236
	v_sub_f32_e32 v237, 1.0, v237
	v_lshlrev_b32_e32 v238, 16, v150
	v_and_b32_e32 v239, 0xffff0000, v150
	v_lshlrev_b32_e32 v240, 16, v151
	v_and_b32_e32 v241, 0xffff0000, v151
	v_pk_fma_f32 v[2:3], v[2:3], v[234:235], v[238:239]
	v_pk_fma_f32 v[4:5], v[4:5], v[236:237], v[240:241]
	v_pk_mul_f32 v[6:7], v[6:7], v[234:235]
	v_pk_mul_f32 v[8:9], v[8:9], v[236:237]
	global_load_dwordx2 v[232:233], v243, s[0:1]
	ds_write_b128 v11, v[6:9]
	ds_write_b128 v11, v[2:5] offset:8192
	v_mov_b32_e32 v2, 0
	v_mov_b32_e32 v3, 0
	v_mov_b32_e32 v4, 0
	v_mov_b32_e32 v5, 0
	s_waitcnt lgkmcnt(0)
	s_barrier
	s_and_saveexec_b64 s[0:1], s[6:7]
	s_cbranch_execz .Llru_fold_done
	s_mov_b64 s[2:3], 0
	v_mov_b32_e32 v1, v27
	v_mov_b32_e32 v6, v10
.Llru_fold:
	ds_read_b128 v[234:237], v1
	ds_read_b128 v[238:241], v1 offset:8192
	v_add_u32_e32 v6, -1, v6
	v_cmp_eq_u32_e32 vcc, 0, v6
	v_add_u32_e32 v1, 0x80, v1
	s_or_b64 s[2:3], vcc, s[2:3]
	s_waitcnt lgkmcnt(0)
	v_pk_fma_f32 v[4:5], v[4:5], v[236:237], v[240:241]
	v_pk_fma_f32 v[2:3], v[2:3], v[234:235], v[238:239]
	s_andn2_b64 exec, exec, s[2:3]
	s_cbranch_execnz .Llru_fold
	s_or_b64 exec, exec, s[2:3]
; __device__ __forceinline__ unsigned cvt_pk_bf16(float lo, float hi) { unsigned r; asm volatile("v_cvt_pk_bf16_f32 %0, %1, %2" : "=v"(r) : "v"(lo), "v"(hi)); return r; }
; __device__ __forceinline__ float bflo(unsigned w) { return __uint_as_float(w << 16); }
; __device__ __forceinline__ float bfhi(unsigned w) { return __uint_as_float(w & 0xffff0000u); }
; __device__ __forceinline__ void lru_scan_phase(const bf16_t* DD, const bf16_t* BB, const bf16_t* YG, bf16_t* Y, LAS float* sm, int tid, int bid, int G) {
;     ...
; #pragma unroll 8
;         for (int t = 0; t < 32; ++t) { const u32x2 dw = *(const u32x2*)(DD + base + (size_t)t * D), bw = *(const u32x2*)(BB + base + (size_t)t * D); const u32x2 yg = *(const u32x2*)(YG + base + (size_t)t * D);
;             const f32x4 a = (f32x4){1.f - bflo(dw.x), 1.f - bfhi(dw.x), 1.f - bflo(dw.y), 1.f - bfhi(dw.y)}, bv = (f32x4){bflo(bw.x), bfhi(bw.x), bflo(bw.y), bfhi(bw.y)};
;             h = a * h + bv; u32x2 o; o.x = cvt_pk_bf16(h[0] * bflo(yg.x), h[1] * bfhi(yg.x)); o.y = cvt_pk_bf16(h[2] * bflo(yg.y), h[3] * bfhi(yg.y)); *(u32x2*)(Y + base + (size_t)t * D) = o; }
.Llru_fold_done:
	s_or_b64 exec, exec, s[0:1]
	s_add_u32 s2, s38, 0x10c00000
	s_addc_u32 s3, s39, 0
	s_nop 0
	s_waitcnt vmcnt(31)
	v_lshlrev_b32_e32 v234, 16, v16
	v_and_b32_e32 v235, 0xffff0000, v16
	v_lshlrev_b32_e32 v236, 16, v17
	v_and_b32_e32 v237, 0xffff0000, v17
	v_sub_f32_e32 v234, 1.0, v234
	v_sub_f32_e32 v235, 1.0, v235
	v_sub_f32_e32 v236, 1.0, v236
	v_sub_f32_e32 v237, 1.0, v237
	v_lshlrev_b32_e32 v238, 16, v82
	v_and_b32_e32 v239, 0xffff0000, v82
	v_lshlrev_b32_e32 v240, 16, v83
	v_and_b32_e32 v241, 0xffff0000, v83
	v_pk_fma_f32 v[2:3], v[2:3], v[234:235], v[238:239]
	v_pk_fma_f32 v[4:5], v[4:5], v[236:237], v[240:241]
	v_lshlrev_b32_e32 v244, 16, v156
	v_and_b32_e32 v245, 0xffff0000, v156
	v_lshlrev_b32_e32 v246, 16, v157
	v_and_b32_e32 v247, 0xffff0000, v157
	v_mul_f32_e32 v244, v2, v244
	v_mul_f32_e32 v245, v3, v245
	v_mul_f32_e32 v246, v4, v246
	v_mul_f32_e32 v247, v5, v247
	v_cvt_pk_bf16_f32 v248, v244, v245
	v_cvt_pk_bf16_f32 v249, v246, v247
	global_store_dwordx2 v250, v[248:249], s[2:3] offset:-4096
	s_waitcnt vmcnt(31)
	v_lshlrev_b32_e32 v234, 16, v18
	v_and_b32_e32 v235, 0xffff0000, v18
	v_lshlrev_b32_e32 v236, 16, v19
	v_and_b32_e32 v237, 0xffff0000, v19
	v_sub_f32_e32 v234, 1.0, v234
	v_sub_f32_e32 v235, 1.0, v235
	v_sub_f32_e32 v236, 1.0, v236
	v_sub_f32_e32 v237, 1.0, v237
	v_lshlrev_b32_e32 v238, 16, v84
	v_and_b32_e32 v239, 0xffff0000, v84
	v_lshlrev_b32_e32 v240, 16, v85
	v_and_b32_e32 v241, 0xffff0000, v85
	v_pk_fma_f32 v[2:3], v[2:3], v[234:235], v[238:239]
	v_pk_fma_f32 v[4:5], v[4:5], v[236:237], v[240:241]
	v_lshlrev_b32_e32 v244, 16, v158
	v_and_b32_e32 v245, 0xffff0000, v158
	v_lshlrev_b32_e32 v246, 16, v159
	v_and_b32_e32 v247, 0xffff0000, v159
	v_mul_f32_e32 v244, v2, v244
	v_mul_f32_e32 v245, v3, v245
	v_mul_f32_e32 v246, v4, v246
	v_mul_f32_e32 v247, v5, v247
	v_cvt_pk_bf16_f32 v248, v244, v245
	v_cvt_pk_bf16_f32 v249, v246, v247
	global_store_dwordx2 v250, v[248:249], s[2:3]
	v_add_u32_e32 v250, 0x2000, v250
	s_waitcnt vmcnt(31)
	v_lshlrev_b32_e32 v234, 16, v20
	v_and_b32_e32 v235, 0xffff0000, v20
	v_lshlrev_b32_e32 v236, 16, v21
	v_and_b32_e32 v237, 0xffff0000, v21
	v_sub_f32_e32 v234, 1.0, v234
	v_sub_f32_e32 v235, 1.0, v235
	v_sub_f32_e32 v236, 1.0, v236
	v_sub_f32_e32 v237, 1.0, v237
	v_lshlrev_b32_e32 v238, 16, v86
	v_and_b32_e32 v239, 0xffff0000, v86
	v_lshlrev_b32_e32 v240, 16, v87
	v_and_b32_e32 v241, 0xffff0000, v87
	v_pk_fma_f32 v[2:3], v[2:3], v[234:235], v[238:239]
	v_pk_fma_f32 v[4:5], v[4:5], v[236:237], v[240:241]
	v_lshlrev_b32_e32 v244, 16, v160
	v_and_b32_e32 v245, 0xffff0000, v160
	v_lshlrev_b32_e32 v246, 16, v161
	v_and_b32_e32 v247, 0xffff0000, v161
	v_mul_f32_e32 v244, v2, v244
	v_mul_f32_e32 v245, v3, v245
	v_mul_f32_e32 v246, v4, v246
	v_mul_f32_e32 v247, v5, v247
	v_cvt_pk_bf16_f32 v248, v244, v245
	v_cvt_pk_bf16_f32 v249, v246, v247
	global_store_dwordx2 v250, v[248:249], s[2:3] offset:-4096
	s_waitcnt vmcnt(31)
	v_lshlrev_b32_e32 v234, 16, v22
	v_and_b32_e32 v235, 0xffff0000, v22
	v_lshlrev_b32_e32 v236, 16, v23
	v_and_b32_e32 v237, 0xffff0000, v23
	v_sub_f32_e32 v234, 1.0, v234
	v_sub_f32_e32 v235, 1.0, v235
	v_sub_f32_e32 v236, 1.0, v236
	v_sub_f32_e32 v237, 1.0, v237
	v_lshlrev_b32_e32 v238, 16, v88
	v_and_b32_e32 v239, 0xffff0000, v88
	v_lshlrev_b32_e32 v240, 16, v89
	v_and_b32_e32 v241, 0xffff0000, v89
	v_pk_fma_f32 v[2:3], v[2:3], v[234:235], v[238:239]
	v_pk_fma_f32 v[4:5], v[4:5], v[236:237], v[240:241]
	v_lshlrev_b32_e32 v244, 16, v162
	v_and_b32_e32 v245, 0xffff0000, v162
	v_lshlrev_b32_e32 v246, 16, v163
	v_and_b32_e32 v247, 0xffff0000, v163
	v_mul_f32_e32 v244, v2, v244
	v_mul_f32_e32 v245, v3, v245
	v_mul_f32_e32 v246, v4, v246
	v_mul_f32_e32 v247, v5, v247
	v_cvt_pk_bf16_f32 v248, v244, v245
	v_cvt_pk_bf16_f32 v249, v246, v247
	global_store_dwordx2 v250, v[248:249], s[2:3]
	v_add_u32_e32 v250, 0x2000, v250
	s_waitcnt vmcnt(31)
	v_lshlrev_b32_e32 v234, 16, v24
	v_and_b32_e32 v235, 0xffff0000, v24
	v_lshlrev_b32_e32 v236, 16, v25
	v_and_b32_e32 v237, 0xffff0000, v25
	v_sub_f32_e32 v234, 1.0, v234
	v_sub_f32_e32 v235, 1.0, v235
	v_sub_f32_e32 v236, 1.0, v236
	v_sub_f32_e32 v237, 1.0, v237
	v_lshlrev_b32_e32 v238, 16, v90
	v_and_b32_e32 v239, 0xffff0000, v90
	v_lshlrev_b32_e32 v240, 16, v91
	v_and_b32_e32 v241, 0xffff0000, v91
	v_pk_fma_f32 v[2:3], v[2:3], v[234:235], v[238:239]
	v_pk_fma_f32 v[4:5], v[4:5], v[236:237], v[240:241]
	v_lshlrev_b32_e32 v244, 16, v164
	v_and_b32_e32 v245, 0xffff0000, v164
	v_lshlrev_b32_e32 v246, 16, v165
	v_and_b32_e32 v247, 0xffff0000, v165
	v_mul_f32_e32 v244, v2, v244
	v_mul_f32_e32 v245, v3, v245
	v_mul_f32_e32 v246, v4, v246
	v_mul_f32_e32 v247, v5, v247
	v_cvt_pk_bf16_f32 v248, v244, v245
	v_cvt_pk_bf16_f32 v249, v246, v247
	global_store_dwordx2 v250, v[248:249], s[2:3] offset:-4096
	s_waitcnt vmcnt(31)
	v_lshlrev_b32_e32 v234, 16, v28
	v_and_b32_e32 v235, 0xffff0000, v28
	v_lshlrev_b32_e32 v236, 16, v29
	v_and_b32_e32 v237, 0xffff0000, v29
	v_sub_f32_e32 v234, 1.0, v234
	v_sub_f32_e32 v235, 1.0, v235
	v_sub_f32_e32 v236, 1.0, v236
	v_sub_f32_e32 v237, 1.0, v237
	v_lshlrev_b32_e32 v238, 16, v92
	v_and_b32_e32 v239, 0xffff0000, v92
	v_lshlrev_b32_e32 v240, 16, v93
	v_and_b32_e32 v241, 0xffff0000, v93
	v_pk_fma_f32 v[2:3], v[2:3], v[234:235], v[238:239]
	v_pk_fma_f32 v[4:5], v[4:5], v[236:237], v[240:241]
	v_lshlrev_b32_e32 v244, 16, v166
	v_and_b32_e32 v245, 0xffff0000, v166
	v_lshlrev_b32_e32 v246, 16, v167
	v_and_b32_e32 v247, 0xffff0000, v167
	v_mul_f32_e32 v244, v2, v244
	v_mul_f32_e32 v245, v3, v245
	v_mul_f32_e32 v246, v4, v246
	v_mul_f32_e32 v247, v5, v247
	v_cvt_pk_bf16_f32 v248, v244, v245
	v_cvt_pk_bf16_f32 v249, v246, v247
	global_store_dwordx2 v250, v[248:249], s[2:3]
	v_add_u32_e32 v250, 0x2000, v250
	s_waitcnt vmcnt(31)
; __device__ __forceinline__ unsigned cvt_pk_bf16(float lo, float hi) { unsigned r; asm volatile("v_cvt_pk_bf16_f32 %0, %1, %2" : "=v"(r) : "v"(lo), "v"(hi)); return r; }
; __device__ __forceinline__ float bflo(unsigned w) { return __uint_as_float(w << 16); }
; __device__ __forceinline__ float bfhi(unsigned w) { return __uint_as_float(w & 0xffff0000u); }
; __device__ __forceinline__ void lru_scan_phase(const bf16_t* DD, const bf16_t* BB, const bf16_t* YG, bf16_t* Y, LAS float* sm, int tid, int bid, int G) {
;     ...
; #pragma unroll 8
;         for (int t = 0; t < 32; ++t) { const u32x2 dw = *(const u32x2*)(DD + base + (size_t)t * D), bw = *(const u32x2*)(BB + base + (size_t)t * D); const u32x2 yg = *(const u32x2*)(YG + base + (size_t)t * D);
;             const f32x4 a = (f32x4){1.f - bflo(dw.x), 1.f - bfhi(dw.x), 1.f - bflo(dw.y), 1.f - bfhi(dw.y)}, bv = (f32x4){bflo(bw.x), bfhi(bw.x), bflo(bw.y), bfhi(bw.y)};
;             h = a * h + bv; u32x2 o; o.x = cvt_pk_bf16(h[0] * bflo(yg.x), h[1] * bfhi(yg.x)); o.y = cvt_pk_bf16(h[2] * bflo(yg.y), h[3] * bfhi(yg.y)); *(u32x2*)(Y + base + (size_t)t * D) = o; }
	v_lshlrev_b32_e32 v234, 16, v30
	v_and_b32_e32 v235, 0xffff0000, v30
	v_lshlrev_b32_e32 v236, 16, v31
	v_and_b32_e32 v237, 0xffff0000, v31
	v_sub_f32_e32 v234, 1.0, v234
	v_sub_f32_e32 v235, 1.0, v235
	v_sub_f32_e32 v236, 1.0, v236
	v_sub_f32_e32 v237, 1.0, v237
	v_lshlrev_b32_e32 v238, 16, v94
	v_and_b32_e32 v239, 0xffff0000, v94
	v_lshlrev_b32_e32 v240, 16, v95
	v_and_b32_e32 v241, 0xffff0000, v95
	v_pk_fma_f32 v[2:3], v[2:3], v[234:235], v[238:239]
	v_pk_fma_f32 v[4:5], v[4:5], v[236:237], v[240:241]
	v_lshlrev_b32_e32 v244, 16, v168
	v_and_b32_e32 v245, 0xffff0000, v168
	v_lshlrev_b32_e32 v246, 16, v169
	v_and_b32_e32 v247, 0xffff0000, v169
	v_mul_f32_e32 v244, v2, v244
	v_mul_f32_e32 v245, v3, v245
	v_mul_f32_e32 v246, v4, v246
	v_mul_f32_e32 v247, v5, v247
	v_cvt_pk_bf16_f32 v248, v244, v245
	v_cvt_pk_bf16_f32 v249, v246, v247
	global_store_dwordx2 v250, v[248:249], s[2:3] offset:-4096
	s_waitcnt vmcnt(31)
	v_lshlrev_b32_e32 v234, 16, v32
	v_and_b32_e32 v235, 0xffff0000, v32
	v_lshlrev_b32_e32 v236, 16, v33
	v_and_b32_e32 v237, 0xffff0000, v33
	v_sub_f32_e32 v234, 1.0, v234
	v_sub_f32_e32 v235, 1.0, v235
	v_sub_f32_e32 v236, 1.0, v236
	v_sub_f32_e32 v237, 1.0, v237
	v_lshlrev_b32_e32 v238, 16, v96
	v_and_b32_e32 v239, 0xffff0000, v96
	v_lshlrev_b32_e32 v240, 16, v97
	v_and_b32_e32 v241, 0xffff0000, v97
	v_pk_fma_f32 v[2:3], v[2:3], v[234:235], v[238:239]
	v_pk_fma_f32 v[4:5], v[4:5], v[236:237], v[240:241]
	v_lshlrev_b32_e32 v244, 16, v170
	v_and_b32_e32 v245, 0xffff0000, v170
	v_lshlrev_b32_e32 v246, 16, v171
	v_and_b32_e32 v247, 0xffff0000, v171
	v_mul_f32_e32 v244, v2, v244
	v_mul_f32_e32 v245, v3, v245
	v_mul_f32_e32 v246, v4, v246
	v_mul_f32_e32 v247, v5, v247
	v_cvt_pk_bf16_f32 v248, v244, v245
	v_cvt_pk_bf16_f32 v249, v246, v247
	global_store_dwordx2 v250, v[248:249], s[2:3]
	v_add_u32_e32 v250, 0x2000, v250
	s_waitcnt vmcnt(31)
	v_lshlrev_b32_e32 v234, 16, v34
	v_and_b32_e32 v235, 0xffff0000, v34
	v_lshlrev_b32_e32 v236, 16, v35
	v_and_b32_e32 v237, 0xffff0000, v35
	v_sub_f32_e32 v234, 1.0, v234
	v_sub_f32_e32 v235, 1.0, v235
	v_sub_f32_e32 v236, 1.0, v236
	v_sub_f32_e32 v237, 1.0, v237
	v_lshlrev_b32_e32 v238, 16, v98
	v_and_b32_e32 v239, 0xffff0000, v98
	v_lshlrev_b32_e32 v240, 16, v99
	v_and_b32_e32 v241, 0xffff0000, v99
	v_pk_fma_f32 v[2:3], v[2:3], v[234:235], v[238:239]
	v_pk_fma_f32 v[4:5], v[4:5], v[236:237], v[240:241]
	v_lshlrev_b32_e32 v244, 16, v172
	v_and_b32_e32 v245, 0xffff0000, v172
	v_lshlrev_b32_e32 v246, 16, v173
	v_and_b32_e32 v247, 0xffff0000, v173
	v_mul_f32_e32 v244, v2, v244
	v_mul_f32_e32 v245, v3, v245
	v_mul_f32_e32 v246, v4, v246
	v_mul_f32_e32 v247, v5, v247
	v_cvt_pk_bf16_f32 v248, v244, v245
	v_cvt_pk_bf16_f32 v249, v246, v247
	global_store_dwordx2 v250, v[248:249], s[2:3] offset:-4096
	s_waitcnt vmcnt(31)
	v_lshlrev_b32_e32 v234, 16, v36
	v_and_b32_e32 v235, 0xffff0000, v36
	v_lshlrev_b32_e32 v236, 16, v37
	v_and_b32_e32 v237, 0xffff0000, v37
	v_sub_f32_e32 v234, 1.0, v234
	v_sub_f32_e32 v235, 1.0, v235
	v_sub_f32_e32 v236, 1.0, v236
	v_sub_f32_e32 v237, 1.0, v237
	v_lshlrev_b32_e32 v238, 16, v100
	v_and_b32_e32 v239, 0xffff0000, v100
	v_lshlrev_b32_e32 v240, 16, v101
	v_and_b32_e32 v241, 0xffff0000, v101
	v_pk_fma_f32 v[2:3], v[2:3], v[234:235], v[238:239]
	v_pk_fma_f32 v[4:5], v[4:5], v[236:237], v[240:241]
	v_lshlrev_b32_e32 v244, 16, v174
	v_and_b32_e32 v245, 0xffff0000, v174
	v_lshlrev_b32_e32 v246, 16, v175
	v_and_b32_e32 v247, 0xffff0000, v175
	v_mul_f32_e32 v244, v2, v244
	v_mul_f32_e32 v245, v3, v245
	v_mul_f32_e32 v246, v4, v246
	v_mul_f32_e32 v247, v5, v247
	v_cvt_pk_bf16_f32 v248, v244, v245
	v_cvt_pk_bf16_f32 v249, v246, v247
	global_store_dwordx2 v250, v[248:249], s[2:3]
	v_add_u32_e32 v250, 0x2000, v250
	s_waitcnt vmcnt(31)
	v_lshlrev_b32_e32 v234, 16, v38
	v_and_b32_e32 v235, 0xffff0000, v38
	v_lshlrev_b32_e32 v236, 16, v39
	v_and_b32_e32 v237, 0xffff0000, v39
	v_sub_f32_e32 v234, 1.0, v234
	v_sub_f32_e32 v235, 1.0, v235
	v_sub_f32_e32 v236, 1.0, v236
	v_sub_f32_e32 v237, 1.0, v237
	v_lshlrev_b32_e32 v238, 16, v102
	v_and_b32_e32 v239, 0xffff0000, v102
	v_lshlrev_b32_e32 v240, 16, v103
	v_and_b32_e32 v241, 0xffff0000, v103
	v_pk_fma_f32 v[2:3], v[2:3], v[234:235], v[238:239]
	v_pk_fma_f32 v[4:5], v[4:5], v[236:237], v[240:241]
	v_lshlrev_b32_e32 v244, 16, v176
	v_and_b32_e32 v245, 0xffff0000, v176
	v_lshlrev_b32_e32 v246, 16, v177
	v_and_b32_e32 v247, 0xffff0000, v177
	v_mul_f32_e32 v244, v2, v244
	v_mul_f32_e32 v245, v3, v245
	v_mul_f32_e32 v246, v4, v246
	v_mul_f32_e32 v247, v5, v247
	v_cvt_pk_bf16_f32 v248, v244, v245
	v_cvt_pk_bf16_f32 v249, v246, v247
	global_store_dwordx2 v250, v[248:249], s[2:3] offset:-4096
	s_waitcnt vmcnt(31)
	v_lshlrev_b32_e32 v234, 16, v40
	v_and_b32_e32 v235, 0xffff0000, v40
	v_lshlrev_b32_e32 v236, 16, v41
	v_and_b32_e32 v237, 0xffff0000, v41
	v_sub_f32_e32 v234, 1.0, v234
	v_sub_f32_e32 v235, 1.0, v235
	v_sub_f32_e32 v236, 1.0, v236
	v_sub_f32_e32 v237, 1.0, v237
	v_lshlrev_b32_e32 v238, 16, v104
	v_and_b32_e32 v239, 0xffff0000, v104
	v_lshlrev_b32_e32 v240, 16, v105
	v_and_b32_e32 v241, 0xffff0000, v105
	v_pk_fma_f32 v[2:3], v[2:3], v[234:235], v[238:239]
	v_pk_fma_f32 v[4:5], v[4:5], v[236:237], v[240:241]
	v_lshlrev_b32_e32 v244, 16, v178
	v_and_b32_e32 v245, 0xffff0000, v178
	v_lshlrev_b32_e32 v246, 16, v179
	v_and_b32_e32 v247, 0xffff0000, v179
	v_mul_f32_e32 v244, v2, v244
	v_mul_f32_e32 v245, v3, v245
	v_mul_f32_e32 v246, v4, v246
	v_mul_f32_e32 v247, v5, v247
	v_cvt_pk_bf16_f32 v248, v244, v245
	v_cvt_pk_bf16_f32 v249, v246, v247
	global_store_dwordx2 v250, v[248:249], s[2:3]
	v_add_u32_e32 v250, 0x2000, v250
	s_waitcnt vmcnt(31)
; __device__ __forceinline__ unsigned cvt_pk_bf16(float lo, float hi) { unsigned r; asm volatile("v_cvt_pk_bf16_f32 %0, %1, %2" : "=v"(r) : "v"(lo), "v"(hi)); return r; }
; __device__ __forceinline__ float bflo(unsigned w) { return __uint_as_float(w << 16); }
; __device__ __forceinline__ float bfhi(unsigned w) { return __uint_as_float(w & 0xffff0000u); }
; __device__ __forceinline__ void lru_scan_phase(const bf16_t* DD, const bf16_t* BB, const bf16_t* YG, bf16_t* Y, LAS float* sm, int tid, int bid, int G) {
;     ...
; #pragma unroll 8
;         for (int t = 0; t < 32; ++t) { const u32x2 dw = *(const u32x2*)(DD + base + (size_t)t * D), bw = *(const u32x2*)(BB + base + (size_t)t * D); const u32x2 yg = *(const u32x2*)(YG + base + (size_t)t * D);
;             const f32x4 a = (f32x4){1.f - bflo(dw.x), 1.f - bfhi(dw.x), 1.f - bflo(dw.y), 1.f - bfhi(dw.y)}, bv = (f32x4){bflo(bw.x), bfhi(bw.x), bflo(bw.y), bfhi(bw.y)};
;             h = a * h + bv; u32x2 o; o.x = cvt_pk_bf16(h[0] * bflo(yg.x), h[1] * bfhi(yg.x)); o.y = cvt_pk_bf16(h[2] * bflo(yg.y), h[3] * bfhi(yg.y)); *(u32x2*)(Y + base + (size_t)t * D) = o; }
	v_lshlrev_b32_e32 v234, 16, v42
	v_and_b32_e32 v235, 0xffff0000, v42
	v_lshlrev_b32_e32 v236, 16, v43
	v_and_b32_e32 v237, 0xffff0000, v43
	v_sub_f32_e32 v234, 1.0, v234
	v_sub_f32_e32 v235, 1.0, v235
	v_sub_f32_e32 v236, 1.0, v236
	v_sub_f32_e32 v237, 1.0, v237
	v_lshlrev_b32_e32 v238, 16, v106
	v_and_b32_e32 v239, 0xffff0000, v106
	v_lshlrev_b32_e32 v240, 16, v107
	v_and_b32_e32 v241, 0xffff0000, v107
	v_pk_fma_f32 v[2:3], v[2:3], v[234:235], v[238:239]
	v_pk_fma_f32 v[4:5], v[4:5], v[236:237], v[240:241]
	v_lshlrev_b32_e32 v244, 16, v180
	v_and_b32_e32 v245, 0xffff0000, v180
	v_lshlrev_b32_e32 v246, 16, v181
	v_and_b32_e32 v247, 0xffff0000, v181
	v_mul_f32_e32 v244, v2, v244
	v_mul_f32_e32 v245, v3, v245
	v_mul_f32_e32 v246, v4, v246
	v_mul_f32_e32 v247, v5, v247
	v_cvt_pk_bf16_f32 v248, v244, v245
	v_cvt_pk_bf16_f32 v249, v246, v247
	global_store_dwordx2 v250, v[248:249], s[2:3] offset:-4096
	s_waitcnt vmcnt(31)
	v_lshlrev_b32_e32 v234, 16, v44
	v_and_b32_e32 v235, 0xffff0000, v44
	v_lshlrev_b32_e32 v236, 16, v45
	v_and_b32_e32 v237, 0xffff0000, v45
	v_sub_f32_e32 v234, 1.0, v234
	v_sub_f32_e32 v235, 1.0, v235
	v_sub_f32_e32 v236, 1.0, v236
	v_sub_f32_e32 v237, 1.0, v237
	v_lshlrev_b32_e32 v238, 16, v108
	v_and_b32_e32 v239, 0xffff0000, v108
	v_lshlrev_b32_e32 v240, 16, v109
	v_and_b32_e32 v241, 0xffff0000, v109
	v_pk_fma_f32 v[2:3], v[2:3], v[234:235], v[238:239]
	v_pk_fma_f32 v[4:5], v[4:5], v[236:237], v[240:241]
	v_lshlrev_b32_e32 v244, 16, v182
	v_and_b32_e32 v245, 0xffff0000, v182
	v_lshlrev_b32_e32 v246, 16, v183
	v_and_b32_e32 v247, 0xffff0000, v183
	v_mul_f32_e32 v244, v2, v244
	v_mul_f32_e32 v245, v3, v245
	v_mul_f32_e32 v246, v4, v246
	v_mul_f32_e32 v247, v5, v247
	v_cvt_pk_bf16_f32 v248, v244, v245
	v_cvt_pk_bf16_f32 v249, v246, v247
	global_store_dwordx2 v250, v[248:249], s[2:3]
	v_add_u32_e32 v250, 0x2000, v250
	s_waitcnt vmcnt(31)
	v_lshlrev_b32_e32 v234, 16, v46
	v_and_b32_e32 v235, 0xffff0000, v46
	v_lshlrev_b32_e32 v236, 16, v47
	v_and_b32_e32 v237, 0xffff0000, v47
	v_sub_f32_e32 v234, 1.0, v234
	v_sub_f32_e32 v235, 1.0, v235
	v_sub_f32_e32 v236, 1.0, v236
	v_sub_f32_e32 v237, 1.0, v237
	v_lshlrev_b32_e32 v238, 16, v110
	v_and_b32_e32 v239, 0xffff0000, v110
	v_lshlrev_b32_e32 v240, 16, v111
	v_and_b32_e32 v241, 0xffff0000, v111
	v_pk_fma_f32 v[2:3], v[2:3], v[234:235], v[238:239]
	v_pk_fma_f32 v[4:5], v[4:5], v[236:237], v[240:241]
	v_lshlrev_b32_e32 v244, 16, v184
	v_and_b32_e32 v245, 0xffff0000, v184
	v_lshlrev_b32_e32 v246, 16, v185
	v_and_b32_e32 v247, 0xffff0000, v185
	v_mul_f32_e32 v244, v2, v244
	v_mul_f32_e32 v245, v3, v245
	v_mul_f32_e32 v246, v4, v246
	v_mul_f32_e32 v247, v5, v247
	v_cvt_pk_bf16_f32 v248, v244, v245
	v_cvt_pk_bf16_f32 v249, v246, v247
	global_store_dwordx2 v250, v[248:249], s[2:3] offset:-4096
	s_waitcnt vmcnt(31)
	v_lshlrev_b32_e32 v234, 16, v48
	v_and_b32_e32 v235, 0xffff0000, v48
	v_lshlrev_b32_e32 v236, 16, v49
	v_and_b32_e32 v237, 0xffff0000, v49
	v_sub_f32_e32 v234, 1.0, v234
	v_sub_f32_e32 v235, 1.0, v235
	v_sub_f32_e32 v236, 1.0, v236
	v_sub_f32_e32 v237, 1.0, v237
	v_lshlrev_b32_e32 v238, 16, v112
	v_and_b32_e32 v239, 0xffff0000, v112
	v_lshlrev_b32_e32 v240, 16, v113
	v_and_b32_e32 v241, 0xffff0000, v113
	v_pk_fma_f32 v[2:3], v[2:3], v[234:235], v[238:239]
	v_pk_fma_f32 v[4:5], v[4:5], v[236:237], v[240:241]
	v_lshlrev_b32_e32 v244, 16, v186
	v_and_b32_e32 v245, 0xffff0000, v186
	v_lshlrev_b32_e32 v246, 16, v187
	v_and_b32_e32 v247, 0xffff0000, v187
	v_mul_f32_e32 v244, v2, v244
	v_mul_f32_e32 v245, v3, v245
	v_mul_f32_e32 v246, v4, v246
	v_mul_f32_e32 v247, v5, v247
	v_cvt_pk_bf16_f32 v248, v244, v245
	v_cvt_pk_bf16_f32 v249, v246, v247
	global_store_dwordx2 v250, v[248:249], s[2:3]
	v_add_u32_e32 v250, 0x2000, v250
	s_waitcnt vmcnt(31)
	v_lshlrev_b32_e32 v234, 16, v50
	v_and_b32_e32 v235, 0xffff0000, v50
	v_lshlrev_b32_e32 v236, 16, v51
	v_and_b32_e32 v237, 0xffff0000, v51
	v_sub_f32_e32 v234, 1.0, v234
	v_sub_f32_e32 v235, 1.0, v235
	v_sub_f32_e32 v236, 1.0, v236
	v_sub_f32_e32 v237, 1.0, v237
	v_lshlrev_b32_e32 v238, 16, v114
	v_and_b32_e32 v239, 0xffff0000, v114
	v_lshlrev_b32_e32 v240, 16, v115
	v_and_b32_e32 v241, 0xffff0000, v115
	v_pk_fma_f32 v[2:3], v[2:3], v[234:235], v[238:239]
	v_pk_fma_f32 v[4:5], v[4:5], v[236:237], v[240:241]
	v_lshlrev_b32_e32 v244, 16, v188
	v_and_b32_e32 v245, 0xffff0000, v188
	v_lshlrev_b32_e32 v246, 16, v189
	v_and_b32_e32 v247, 0xffff0000, v189
	v_mul_f32_e32 v244, v2, v244
	v_mul_f32_e32 v245, v3, v245
	v_mul_f32_e32 v246, v4, v246
	v_mul_f32_e32 v247, v5, v247
	v_cvt_pk_bf16_f32 v248, v244, v245
	v_cvt_pk_bf16_f32 v249, v246, v247
	global_store_dwordx2 v250, v[248:249], s[2:3] offset:-4096
	s_waitcnt vmcnt(31)
	v_lshlrev_b32_e32 v234, 16, v52
	v_and_b32_e32 v235, 0xffff0000, v52
	v_lshlrev_b32_e32 v236, 16, v53
	v_and_b32_e32 v237, 0xffff0000, v53
	v_sub_f32_e32 v234, 1.0, v234
	v_sub_f32_e32 v235, 1.0, v235
	v_sub_f32_e32 v236, 1.0, v236
	v_sub_f32_e32 v237, 1.0, v237
	v_lshlrev_b32_e32 v238, 16, v116
	v_and_b32_e32 v239, 0xffff0000, v116
	v_lshlrev_b32_e32 v240, 16, v117
	v_and_b32_e32 v241, 0xffff0000, v117
	v_pk_fma_f32 v[2:3], v[2:3], v[234:235], v[238:239]
	v_pk_fma_f32 v[4:5], v[4:5], v[236:237], v[240:241]
	v_lshlrev_b32_e32 v244, 16, v190
	v_and_b32_e32 v245, 0xffff0000, v190
	v_lshlrev_b32_e32 v246, 16, v191
	v_and_b32_e32 v247, 0xffff0000, v191
	v_mul_f32_e32 v244, v2, v244
	v_mul_f32_e32 v245, v3, v245
	v_mul_f32_e32 v246, v4, v246
	v_mul_f32_e32 v247, v5, v247
	v_cvt_pk_bf16_f32 v248, v244, v245
	v_cvt_pk_bf16_f32 v249, v246, v247
	global_store_dwordx2 v250, v[248:249], s[2:3]
	v_add_u32_e32 v250, 0x2000, v250
	s_waitcnt vmcnt(31)
; __device__ __forceinline__ unsigned cvt_pk_bf16(float lo, float hi) { unsigned r; asm volatile("v_cvt_pk_bf16_f32 %0, %1, %2" : "=v"(r) : "v"(lo), "v"(hi)); return r; }
; __device__ __forceinline__ float bflo(unsigned w) { return __uint_as_float(w << 16); }
; __device__ __forceinline__ float bfhi(unsigned w) { return __uint_as_float(w & 0xffff0000u); }
; __device__ __forceinline__ void lru_scan_phase(const bf16_t* DD, const bf16_t* BB, const bf16_t* YG, bf16_t* Y, LAS float* sm, int tid, int bid, int G) {
;     ...
; #pragma unroll 8
;         for (int t = 0; t < 32; ++t) { const u32x2 dw = *(const u32x2*)(DD + base + (size_t)t * D), bw = *(const u32x2*)(BB + base + (size_t)t * D); const u32x2 yg = *(const u32x2*)(YG + base + (size_t)t * D);
;             const f32x4 a = (f32x4){1.f - bflo(dw.x), 1.f - bfhi(dw.x), 1.f - bflo(dw.y), 1.f - bfhi(dw.y)}, bv = (f32x4){bflo(bw.x), bfhi(bw.x), bflo(bw.y), bfhi(bw.y)};
;             h = a * h + bv; u32x2 o; o.x = cvt_pk_bf16(h[0] * bflo(yg.x), h[1] * bfhi(yg.x)); o.y = cvt_pk_bf16(h[2] * bflo(yg.y), h[3] * bfhi(yg.y)); *(u32x2*)(Y + base + (size_t)t * D) = o; }
	v_lshlrev_b32_e32 v234, 16, v54
	v_and_b32_e32 v235, 0xffff0000, v54
	v_lshlrev_b32_e32 v236, 16, v55
	v_and_b32_e32 v237, 0xffff0000, v55
	v_sub_f32_e32 v234, 1.0, v234
	v_sub_f32_e32 v235, 1.0, v235
	v_sub_f32_e32 v236, 1.0, v236
	v_sub_f32_e32 v237, 1.0, v237
	v_lshlrev_b32_e32 v238, 16, v118
	v_and_b32_e32 v239, 0xffff0000, v118
	v_lshlrev_b32_e32 v240, 16, v119
	v_and_b32_e32 v241, 0xffff0000, v119
	v_pk_fma_f32 v[2:3], v[2:3], v[234:235], v[238:239]
	v_pk_fma_f32 v[4:5], v[4:5], v[236:237], v[240:241]
	v_lshlrev_b32_e32 v244, 16, v192
	v_and_b32_e32 v245, 0xffff0000, v192
	v_lshlrev_b32_e32 v246, 16, v193
	v_and_b32_e32 v247, 0xffff0000, v193
	v_mul_f32_e32 v244, v2, v244
	v_mul_f32_e32 v245, v3, v245
	v_mul_f32_e32 v246, v4, v246
	v_mul_f32_e32 v247, v5, v247
	v_cvt_pk_bf16_f32 v248, v244, v245
	v_cvt_pk_bf16_f32 v249, v246, v247
	global_store_dwordx2 v250, v[248:249], s[2:3] offset:-4096
	s_waitcnt vmcnt(31)
	v_lshlrev_b32_e32 v234, 16, v56
	v_and_b32_e32 v235, 0xffff0000, v56
	v_lshlrev_b32_e32 v236, 16, v57
	v_and_b32_e32 v237, 0xffff0000, v57
	v_sub_f32_e32 v234, 1.0, v234
	v_sub_f32_e32 v235, 1.0, v235
	v_sub_f32_e32 v236, 1.0, v236
	v_sub_f32_e32 v237, 1.0, v237
	v_lshlrev_b32_e32 v238, 16, v120
	v_and_b32_e32 v239, 0xffff0000, v120
	v_lshlrev_b32_e32 v240, 16, v121
	v_and_b32_e32 v241, 0xffff0000, v121
	v_pk_fma_f32 v[2:3], v[2:3], v[234:235], v[238:239]
	v_pk_fma_f32 v[4:5], v[4:5], v[236:237], v[240:241]
	v_lshlrev_b32_e32 v244, 16, v194
	v_and_b32_e32 v245, 0xffff0000, v194
	v_lshlrev_b32_e32 v246, 16, v195
	v_and_b32_e32 v247, 0xffff0000, v195
	v_mul_f32_e32 v244, v2, v244
	v_mul_f32_e32 v245, v3, v245
	v_mul_f32_e32 v246, v4, v246
	v_mul_f32_e32 v247, v5, v247
	v_cvt_pk_bf16_f32 v248, v244, v245
	v_cvt_pk_bf16_f32 v249, v246, v247
	global_store_dwordx2 v250, v[248:249], s[2:3]
	v_add_u32_e32 v250, 0x2000, v250
	s_waitcnt vmcnt(31)
	v_lshlrev_b32_e32 v234, 16, v58
	v_and_b32_e32 v235, 0xffff0000, v58
	v_lshlrev_b32_e32 v236, 16, v59
	v_and_b32_e32 v237, 0xffff0000, v59
	v_sub_f32_e32 v234, 1.0, v234
	v_sub_f32_e32 v235, 1.0, v235
	v_sub_f32_e32 v236, 1.0, v236
	v_sub_f32_e32 v237, 1.0, v237
	v_lshlrev_b32_e32 v238, 16, v122
	v_and_b32_e32 v239, 0xffff0000, v122
	v_lshlrev_b32_e32 v240, 16, v123
	v_and_b32_e32 v241, 0xffff0000, v123
	v_pk_fma_f32 v[2:3], v[2:3], v[234:235], v[238:239]
	v_pk_fma_f32 v[4:5], v[4:5], v[236:237], v[240:241]
	v_lshlrev_b32_e32 v244, 16, v198
	v_and_b32_e32 v245, 0xffff0000, v198
	v_lshlrev_b32_e32 v246, 16, v199
	v_and_b32_e32 v247, 0xffff0000, v199
	v_mul_f32_e32 v244, v2, v244
	v_mul_f32_e32 v245, v3, v245
	v_mul_f32_e32 v246, v4, v246
	v_mul_f32_e32 v247, v5, v247
	v_cvt_pk_bf16_f32 v248, v244, v245
	v_cvt_pk_bf16_f32 v249, v246, v247
	global_store_dwordx2 v250, v[248:249], s[2:3] offset:-4096
	s_waitcnt vmcnt(31)
	v_lshlrev_b32_e32 v234, 16, v60
	v_and_b32_e32 v235, 0xffff0000, v60
	v_lshlrev_b32_e32 v236, 16, v61
	v_and_b32_e32 v237, 0xffff0000, v61
	v_sub_f32_e32 v234, 1.0, v234
	v_sub_f32_e32 v235, 1.0, v235
	v_sub_f32_e32 v236, 1.0, v236
	v_sub_f32_e32 v237, 1.0, v237
	v_lshlrev_b32_e32 v238, 16, v124
	v_and_b32_e32 v239, 0xffff0000, v124
	v_lshlrev_b32_e32 v240, 16, v125
	v_and_b32_e32 v241, 0xffff0000, v125
	v_pk_fma_f32 v[2:3], v[2:3], v[234:235], v[238:239]
	v_pk_fma_f32 v[4:5], v[4:5], v[236:237], v[240:241]
	v_lshlrev_b32_e32 v244, 16, v204
	v_and_b32_e32 v245, 0xffff0000, v204
	v_lshlrev_b32_e32 v246, 16, v205
	v_and_b32_e32 v247, 0xffff0000, v205
	v_mul_f32_e32 v244, v2, v244
	v_mul_f32_e32 v245, v3, v245
	v_mul_f32_e32 v246, v4, v246
	v_mul_f32_e32 v247, v5, v247
	v_cvt_pk_bf16_f32 v248, v244, v245
	v_cvt_pk_bf16_f32 v249, v246, v247
	global_store_dwordx2 v250, v[248:249], s[2:3]
	v_add_u32_e32 v250, 0x2000, v250
	s_waitcnt vmcnt(31)
	v_lshlrev_b32_e32 v234, 16, v62
	v_and_b32_e32 v235, 0xffff0000, v62
	v_lshlrev_b32_e32 v236, 16, v63
	v_and_b32_e32 v237, 0xffff0000, v63
	v_sub_f32_e32 v234, 1.0, v234
	v_sub_f32_e32 v235, 1.0, v235
	v_sub_f32_e32 v236, 1.0, v236
	v_sub_f32_e32 v237, 1.0, v237
	v_lshlrev_b32_e32 v238, 16, v126
	v_and_b32_e32 v239, 0xffff0000, v126
	v_lshlrev_b32_e32 v240, 16, v127
	v_and_b32_e32 v241, 0xffff0000, v127
	v_pk_fma_f32 v[2:3], v[2:3], v[234:235], v[238:239]
	v_pk_fma_f32 v[4:5], v[4:5], v[236:237], v[240:241]
	v_lshlrev_b32_e32 v244, 16, v214
	v_and_b32_e32 v245, 0xffff0000, v214
	v_lshlrev_b32_e32 v246, 16, v215
	v_and_b32_e32 v247, 0xffff0000, v215
	v_mul_f32_e32 v244, v2, v244
	v_mul_f32_e32 v245, v3, v245
	v_mul_f32_e32 v246, v4, v246
	v_mul_f32_e32 v247, v5, v247
	v_cvt_pk_bf16_f32 v248, v244, v245
	v_cvt_pk_bf16_f32 v249, v246, v247
	global_store_dwordx2 v250, v[248:249], s[2:3] offset:-4096
	s_waitcnt vmcnt(31)
	v_lshlrev_b32_e32 v234, 16, v64
	v_and_b32_e32 v235, 0xffff0000, v64
	v_lshlrev_b32_e32 v236, 16, v65
	v_and_b32_e32 v237, 0xffff0000, v65
	v_sub_f32_e32 v234, 1.0, v234
	v_sub_f32_e32 v235, 1.0, v235
	v_sub_f32_e32 v236, 1.0, v236
	v_sub_f32_e32 v237, 1.0, v237
	v_lshlrev_b32_e32 v238, 16, v128
	v_and_b32_e32 v239, 0xffff0000, v128
	v_lshlrev_b32_e32 v240, 16, v129
	v_and_b32_e32 v241, 0xffff0000, v129
	v_pk_fma_f32 v[2:3], v[2:3], v[234:235], v[238:239]
	v_pk_fma_f32 v[4:5], v[4:5], v[236:237], v[240:241]
	v_lshlrev_b32_e32 v244, 16, v216
	v_and_b32_e32 v245, 0xffff0000, v216
	v_lshlrev_b32_e32 v246, 16, v217
	v_and_b32_e32 v247, 0xffff0000, v217
	v_mul_f32_e32 v244, v2, v244
	v_mul_f32_e32 v245, v3, v245
	v_mul_f32_e32 v246, v4, v246
	v_mul_f32_e32 v247, v5, v247
	v_cvt_pk_bf16_f32 v248, v244, v245
	v_cvt_pk_bf16_f32 v249, v246, v247
	global_store_dwordx2 v250, v[248:249], s[2:3]
	v_add_u32_e32 v250, 0x2000, v250
	s_waitcnt vmcnt(31)
; __device__ __forceinline__ unsigned cvt_pk_bf16(float lo, float hi) { unsigned r; asm volatile("v_cvt_pk_bf16_f32 %0, %1, %2" : "=v"(r) : "v"(lo), "v"(hi)); return r; }
; __device__ __forceinline__ float bflo(unsigned w) { return __uint_as_float(w << 16); }
; __device__ __forceinline__ float bfhi(unsigned w) { return __uint_as_float(w & 0xffff0000u); }
; __device__ __forceinline__ void lru_scan_phase(const bf16_t* DD, const bf16_t* BB, const bf16_t* YG, bf16_t* Y, LAS float* sm, int tid, int bid, int G) {
;     ...
; #pragma unroll 8
;         for (int t = 0; t < 32; ++t) { const u32x2 dw = *(const u32x2*)(DD + base + (size_t)t * D), bw = *(const u32x2*)(BB + base + (size_t)t * D); const u32x2 yg = *(const u32x2*)(YG + base + (size_t)t * D);
;             const f32x4 a = (f32x4){1.f - bflo(dw.x), 1.f - bfhi(dw.x), 1.f - bflo(dw.y), 1.f - bfhi(dw.y)}, bv = (f32x4){bflo(bw.x), bfhi(bw.x), bflo(bw.y), bfhi(bw.y)};
;             h = a * h + bv; u32x2 o; o.x = cvt_pk_bf16(h[0] * bflo(yg.x), h[1] * bfhi(yg.x)); o.y = cvt_pk_bf16(h[2] * bflo(yg.y), h[3] * bfhi(yg.y)); *(u32x2*)(Y + base + (size_t)t * D) = o; }
	v_lshlrev_b32_e32 v234, 16, v66
	v_and_b32_e32 v235, 0xffff0000, v66
	v_lshlrev_b32_e32 v236, 16, v67
	v_and_b32_e32 v237, 0xffff0000, v67
	v_sub_f32_e32 v234, 1.0, v234
	v_sub_f32_e32 v235, 1.0, v235
	v_sub_f32_e32 v236, 1.0, v236
	v_sub_f32_e32 v237, 1.0, v237
	v_lshlrev_b32_e32 v238, 16, v130
	v_and_b32_e32 v239, 0xffff0000, v130
	v_lshlrev_b32_e32 v240, 16, v131
	v_and_b32_e32 v241, 0xffff0000, v131
	v_pk_fma_f32 v[2:3], v[2:3], v[234:235], v[238:239]
	v_pk_fma_f32 v[4:5], v[4:5], v[236:237], v[240:241]
	v_lshlrev_b32_e32 v244, 16, v218
	v_and_b32_e32 v245, 0xffff0000, v218
	v_lshlrev_b32_e32 v246, 16, v219
	v_and_b32_e32 v247, 0xffff0000, v219
	v_mul_f32_e32 v244, v2, v244
	v_mul_f32_e32 v245, v3, v245
	v_mul_f32_e32 v246, v4, v246
	v_mul_f32_e32 v247, v5, v247
	v_cvt_pk_bf16_f32 v248, v244, v245
	v_cvt_pk_bf16_f32 v249, v246, v247
	global_store_dwordx2 v250, v[248:249], s[2:3] offset:-4096
	s_waitcnt vmcnt(31)
	v_lshlrev_b32_e32 v234, 16, v68
	v_and_b32_e32 v235, 0xffff0000, v68
	v_lshlrev_b32_e32 v236, 16, v69
	v_and_b32_e32 v237, 0xffff0000, v69
	v_sub_f32_e32 v234, 1.0, v234
	v_sub_f32_e32 v235, 1.0, v235
	v_sub_f32_e32 v236, 1.0, v236
	v_sub_f32_e32 v237, 1.0, v237
	v_lshlrev_b32_e32 v238, 16, v132
	v_and_b32_e32 v239, 0xffff0000, v132
	v_lshlrev_b32_e32 v240, 16, v133
	v_and_b32_e32 v241, 0xffff0000, v133
	v_pk_fma_f32 v[2:3], v[2:3], v[234:235], v[238:239]
	v_pk_fma_f32 v[4:5], v[4:5], v[236:237], v[240:241]
	v_lshlrev_b32_e32 v244, 16, v220
	v_and_b32_e32 v245, 0xffff0000, v220
	v_lshlrev_b32_e32 v246, 16, v221
	v_and_b32_e32 v247, 0xffff0000, v221
	v_mul_f32_e32 v244, v2, v244
	v_mul_f32_e32 v245, v3, v245
	v_mul_f32_e32 v246, v4, v246
	v_mul_f32_e32 v247, v5, v247
	v_cvt_pk_bf16_f32 v248, v244, v245
	v_cvt_pk_bf16_f32 v249, v246, v247
	global_store_dwordx2 v250, v[248:249], s[2:3]
	v_add_u32_e32 v250, 0x2000, v250
	s_waitcnt vmcnt(31)
	v_lshlrev_b32_e32 v234, 16, v70
	v_and_b32_e32 v235, 0xffff0000, v70
	v_lshlrev_b32_e32 v236, 16, v71
	v_and_b32_e32 v237, 0xffff0000, v71
	v_sub_f32_e32 v234, 1.0, v234
	v_sub_f32_e32 v235, 1.0, v235
	v_sub_f32_e32 v236, 1.0, v236
	v_sub_f32_e32 v237, 1.0, v237
	v_lshlrev_b32_e32 v238, 16, v134
	v_and_b32_e32 v239, 0xffff0000, v134
	v_lshlrev_b32_e32 v240, 16, v135
	v_and_b32_e32 v241, 0xffff0000, v135
	v_pk_fma_f32 v[2:3], v[2:3], v[234:235], v[238:239]
	v_pk_fma_f32 v[4:5], v[4:5], v[236:237], v[240:241]
	v_lshlrev_b32_e32 v244, 16, v222
	v_and_b32_e32 v245, 0xffff0000, v222
	v_lshlrev_b32_e32 v246, 16, v223
	v_and_b32_e32 v247, 0xffff0000, v223
	v_mul_f32_e32 v244, v2, v244
	v_mul_f32_e32 v245, v3, v245
	v_mul_f32_e32 v246, v4, v246
	v_mul_f32_e32 v247, v5, v247
	v_cvt_pk_bf16_f32 v248, v244, v245
	v_cvt_pk_bf16_f32 v249, v246, v247
	global_store_dwordx2 v250, v[248:249], s[2:3] offset:-4096
	s_waitcnt vmcnt(31)
	v_lshlrev_b32_e32 v234, 16, v72
	v_and_b32_e32 v235, 0xffff0000, v72
	v_lshlrev_b32_e32 v236, 16, v73
	v_and_b32_e32 v237, 0xffff0000, v73
	v_sub_f32_e32 v234, 1.0, v234
	v_sub_f32_e32 v235, 1.0, v235
	v_sub_f32_e32 v236, 1.0, v236
	v_sub_f32_e32 v237, 1.0, v237
	v_lshlrev_b32_e32 v238, 16, v136
	v_and_b32_e32 v239, 0xffff0000, v136
	v_lshlrev_b32_e32 v240, 16, v137
	v_and_b32_e32 v241, 0xffff0000, v137
	v_pk_fma_f32 v[2:3], v[2:3], v[234:235], v[238:239]
	v_pk_fma_f32 v[4:5], v[4:5], v[236:237], v[240:241]
	v_lshlrev_b32_e32 v244, 16, v224
	v_and_b32_e32 v245, 0xffff0000, v224
	v_lshlrev_b32_e32 v246, 16, v225
	v_and_b32_e32 v247, 0xffff0000, v225
	v_mul_f32_e32 v244, v2, v244
	v_mul_f32_e32 v245, v3, v245
	v_mul_f32_e32 v246, v4, v246
	v_mul_f32_e32 v247, v5, v247
	v_cvt_pk_bf16_f32 v248, v244, v245
	v_cvt_pk_bf16_f32 v249, v246, v247
	global_store_dwordx2 v250, v[248:249], s[2:3]
	v_add_u32_e32 v250, 0x2000, v250
	s_waitcnt vmcnt(31)
; __device__ __forceinline__ unsigned cvt_pk_bf16(float lo, float hi) { unsigned r; asm volatile("v_cvt_pk_bf16_f32 %0, %1, %2" : "=v"(r) : "v"(lo), "v"(hi)); return r; }
; __device__ __forceinline__ float bflo(unsigned w) { return __uint_as_float(w << 16); }
; __device__ __forceinline__ float bfhi(unsigned w) { return __uint_as_float(w & 0xffff0000u); }
; __device__ __forceinline__ void lru_scan_phase(const bf16_t* DD, const bf16_t* BB, const bf16_t* YG, bf16_t* Y, LAS float* sm, int tid, int bid, int G) {
;     ...
;     for (int w = bid; w < 256; w += G) {
;     ...
;         for (int t = 0; t < 32; ++t) { const u32x2 dw = *(const u32x2*)(DD + base + (size_t)t * D), bw = *(const u32x2*)(BB + base + (size_t)t * D); const u32x2 yg = *(const u32x2*)(YG + base + (size_t)t * D);
;             const f32x4 a = (f32x4){1.f - bflo(dw.x), 1.f - bfhi(dw.x), 1.f - bflo(dw.y), 1.f - bfhi(dw.y)}, bv = (f32x4){bflo(bw.x), bfhi(bw.x), bflo(bw.y), bfhi(bw.y)};
;             h = a * h + bv; u32x2 o; o.x = cvt_pk_bf16(h[0] * bflo(yg.x), h[1] * bfhi(yg.x)); o.y = cvt_pk_bf16(h[2] * bflo(yg.y), h[3] * bfhi(yg.y)); *(u32x2*)(Y + base + (size_t)t * D) = o; }
;         __syncthreads();
;     }
	v_lshlrev_b32_e32 v234, 16, v74
	v_and_b32_e32 v235, 0xffff0000, v74
	v_lshlrev_b32_e32 v236, 16, v75
	v_and_b32_e32 v237, 0xffff0000, v75
	v_sub_f32_e32 v234, 1.0, v234
	v_sub_f32_e32 v235, 1.0, v235
	v_sub_f32_e32 v236, 1.0, v236
	v_sub_f32_e32 v237, 1.0, v237
	v_lshlrev_b32_e32 v238, 16, v138
	v_and_b32_e32 v239, 0xffff0000, v138
	v_lshlrev_b32_e32 v240, 16, v139
	v_and_b32_e32 v241, 0xffff0000, v139
	v_pk_fma_f32 v[2:3], v[2:3], v[234:235], v[238:239]
	v_pk_fma_f32 v[4:5], v[4:5], v[236:237], v[240:241]
	v_lshlrev_b32_e32 v244, 16, v226
	v_and_b32_e32 v245, 0xffff0000, v226
	v_lshlrev_b32_e32 v246, 16, v227
	v_and_b32_e32 v247, 0xffff0000, v227
	v_mul_f32_e32 v244, v2, v244
	v_mul_f32_e32 v245, v3, v245
	v_mul_f32_e32 v246, v4, v246
	v_mul_f32_e32 v247, v5, v247
	v_cvt_pk_bf16_f32 v248, v244, v245
	v_cvt_pk_bf16_f32 v249, v246, v247
	global_store_dwordx2 v250, v[248:249], s[2:3] offset:-4096
	s_waitcnt vmcnt(31)
	v_lshlrev_b32_e32 v234, 16, v76
	v_and_b32_e32 v235, 0xffff0000, v76
	v_lshlrev_b32_e32 v236, 16, v77
	v_and_b32_e32 v237, 0xffff0000, v77
	v_sub_f32_e32 v234, 1.0, v234
	v_sub_f32_e32 v235, 1.0, v235
	v_sub_f32_e32 v236, 1.0, v236
	v_sub_f32_e32 v237, 1.0, v237
	v_lshlrev_b32_e32 v238, 16, v140
	v_and_b32_e32 v239, 0xffff0000, v140
	v_lshlrev_b32_e32 v240, 16, v141
	v_and_b32_e32 v241, 0xffff0000, v141
	v_pk_fma_f32 v[2:3], v[2:3], v[234:235], v[238:239]
	v_pk_fma_f32 v[4:5], v[4:5], v[236:237], v[240:241]
	v_lshlrev_b32_e32 v244, 16, v228
	v_and_b32_e32 v245, 0xffff0000, v228
	v_lshlrev_b32_e32 v246, 16, v229
	v_and_b32_e32 v247, 0xffff0000, v229
	v_mul_f32_e32 v244, v2, v244
	v_mul_f32_e32 v245, v3, v245
	v_mul_f32_e32 v246, v4, v246
	v_mul_f32_e32 v247, v5, v247
	v_cvt_pk_bf16_f32 v248, v244, v245
	v_cvt_pk_bf16_f32 v249, v246, v247
	global_store_dwordx2 v250, v[248:249], s[2:3]
	v_add_u32_e32 v250, 0x2000, v250
	s_waitcnt vmcnt(31)
	v_lshlrev_b32_e32 v234, 16, v78
	v_and_b32_e32 v235, 0xffff0000, v78
	v_lshlrev_b32_e32 v236, 16, v79
	v_and_b32_e32 v237, 0xffff0000, v79
	v_sub_f32_e32 v234, 1.0, v234
	v_sub_f32_e32 v235, 1.0, v235
	v_sub_f32_e32 v236, 1.0, v236
	v_sub_f32_e32 v237, 1.0, v237
	v_lshlrev_b32_e32 v238, 16, v148
	v_and_b32_e32 v239, 0xffff0000, v148
	v_lshlrev_b32_e32 v240, 16, v149
	v_and_b32_e32 v241, 0xffff0000, v149
	v_pk_fma_f32 v[2:3], v[2:3], v[234:235], v[238:239]
	v_pk_fma_f32 v[4:5], v[4:5], v[236:237], v[240:241]
	v_lshlrev_b32_e32 v244, 16, v230
	v_and_b32_e32 v245, 0xffff0000, v230
	v_lshlrev_b32_e32 v246, 16, v231
	v_and_b32_e32 v247, 0xffff0000, v231
	v_mul_f32_e32 v244, v2, v244
	v_mul_f32_e32 v245, v3, v245
	v_mul_f32_e32 v246, v4, v246
	v_mul_f32_e32 v247, v5, v247
	v_cvt_pk_bf16_f32 v248, v244, v245
	v_cvt_pk_bf16_f32 v249, v246, v247
	global_store_dwordx2 v250, v[248:249], s[2:3] offset:-4096
	s_waitcnt vmcnt(31)
	v_lshlrev_b32_e32 v234, 16, v80
	v_and_b32_e32 v235, 0xffff0000, v80
	v_lshlrev_b32_e32 v236, 16, v81
	v_and_b32_e32 v237, 0xffff0000, v81
	v_sub_f32_e32 v234, 1.0, v234
	v_sub_f32_e32 v235, 1.0, v235
	v_sub_f32_e32 v236, 1.0, v236
	v_sub_f32_e32 v237, 1.0, v237
	v_lshlrev_b32_e32 v238, 16, v150
	v_and_b32_e32 v239, 0xffff0000, v150
	v_lshlrev_b32_e32 v240, 16, v151
	v_and_b32_e32 v241, 0xffff0000, v151
	v_pk_fma_f32 v[2:3], v[2:3], v[234:235], v[238:239]
	v_pk_fma_f32 v[4:5], v[4:5], v[236:237], v[240:241]
	v_lshlrev_b32_e32 v244, 16, v232
	v_and_b32_e32 v245, 0xffff0000, v232
	v_lshlrev_b32_e32 v246, 16, v233
	v_and_b32_e32 v247, 0xffff0000, v233
	v_mul_f32_e32 v244, v2, v244
	v_mul_f32_e32 v245, v3, v245
	v_mul_f32_e32 v246, v4, v246
	v_mul_f32_e32 v247, v5, v247
	v_cvt_pk_bf16_f32 v248, v244, v245
	v_cvt_pk_bf16_f32 v249, v246, v247
	global_store_dwordx2 v250, v[248:249], s[2:3]
	v_readlane_b32 s0, v255, 5
	s_add_i32 s10, s10, s0
	s_add_i32 s8, s8, s9
	s_cmpk_gt_i32 s10, 0xff
	s_barrier
	s_cbranch_scc0 .LBB0_469

; __device__ __forceinline__ unsigned cvt_pk_bf16(float lo, float hi) { unsigned r; asm volatile("v_cvt_pk_bf16_f32 %0, %1, %2" : "=v"(r) : "v"(lo), "v"(hi)); return r; }
; __device__ __forceinline__ float bflo(unsigned w) { return __uint_as_float(w << 16); }
; __device__ __forceinline__ float bfhi(unsigned w) { return __uint_as_float(w & 0xffff0000u); }
; __device__ __forceinline__ float fsilu(float x) { return x * fsigmoid(x); }
; template <bool SILU>
; __device__ __forceinline__ void conv_phase(const bf16_t* src, const float* w, const float* b, bf16_t* dst, int C, int gt, int NGT) {
;     ...
;         const bool head = (row0 & (SEQ - 1)) == 0;
;         const bf16_t* sp = src + (size_t)row0 * C + c0;
;         u32x4 x0, x1, x2;
;         if (head) { x0 = (u32x4){0u, 0u, 0u, 0u}; x1 = x0; x2 = x0; }
;         else { x0 = *(const u32x4*)(sp - (size_t)3 * C); x1 = *(const u32x4*)(sp - (size_t)2 * C); x2 = *(const u32x4*)(sp - (size_t)C); }
; #pragma unroll 4
;         for (int r = 0; r < 16; ++r) {
;             const u32x4 x3 = *(const u32x4*)(sp + (size_t)r * C);
;             const unsigned xa[4][4] = {{x0.x, x0.y, x0.z, x0.w}, {x1.x, x1.y, x1.z, x1.w}, {x2.x, x2.y, x2.z, x2.w}, {x3.x, x3.y, x3.z, x3.w}};
;             float a[8];
; #pragma unroll
;             for (int j = 0; j < 8; ++j) a[j] = bs[j];
; #pragma unroll
;             for (int k = 0; k < 4; ++k)
; #pragma unroll
;                 for (int q = 0; q < 4; ++q) { a[2 * q] += wt[k][2 * q] * bflo(xa[k][q]); a[2 * q + 1] += wt[k][2 * q + 1] * bfhi(xa[k][q]); }
;             if (SILU) {
; #pragma unroll
;                 for (int j = 0; j < 8; ++j) a[j] = fsilu(a[j]); }
;             u32x4 o; o.x = cvt_pk_bf16(a[0], a[1]); o.y = cvt_pk_bf16(a[2], a[3]); o.z = cvt_pk_bf16(a[4], a[5]); o.w = cvt_pk_bf16(a[6], a[7]);
;             *(u32x4*)(dst + (size_t)(row0 + r) * C + c0) = o;
.LBB0_516:
	s_or_b64 exec, exec, s[14:15]
	v_lshl_add_u64 v[116:117], s[8:9], 0, v[60:61]
	v_lshl_add_u64 v[116:117], v[58:59], 1, v[116:117]
	global_load_dwordx4 v[100:103], v[116:117], off
	v_add_co_u32_e32 v116, vcc, 0x1000, v116
	s_nop 1
	v_addc_co_u32_e32 v117, vcc, 0, v117, vcc
	global_load_dwordx4 v[104:107], v[116:117], off
	v_add_co_u32_e32 v116, vcc, 0x1000, v116
	s_nop 1
	v_addc_co_u32_e32 v117, vcc, 0, v117, vcc
	global_load_dwordx4 v[108:111], v[116:117], off
	v_add_co_u32_e32 v116, vcc, 0x1000, v116
	s_nop 1
	v_addc_co_u32_e32 v117, vcc, 0, v117, vcc
	global_load_dwordx4 v[112:115], v[116:117], off
	s_waitcnt vmcnt(0)
	v_mov_b32_e32 v56, v48
	v_mov_b32_e32 v57, v12
	v_mov_b32_e32 v12, v49
	v_mov_b32_e32 v48, v40
	v_mov_b32_e32 v49, v8
	v_mov_b32_e32 v8, v41
	v_lshl_add_u64 v[40:41], v[58:59], 1, v[60:61]
	v_mov_b32_e32 v2, v54
	v_mov_b32_e32 v3, v18
	v_mov_b32_e32 v18, v55
	v_mov_b32_e32 v54, v46
	v_mov_b32_e32 v55, v6
	v_mov_b32_e32 v6, v47
	v_mov_b32_e32 v46, v52
	v_mov_b32_e32 v47, v16
	v_mov_b32_e32 v16, v53
	v_mov_b32_e32 v52, v44
	v_mov_b32_e32 v53, v4
	v_mov_b32_e32 v4, v45
	v_mov_b32_e32 v44, v50
	v_mov_b32_e32 v45, v14
	v_mov_b32_e32 v14, v51
	v_mov_b32_e32 v50, v42
	v_mov_b32_e32 v51, v10
	v_mov_b32_e32 v10, v43
	v_lshl_add_u64 v[58:59], s[38:39], 0, v[40:41]
	s_mov_b64 s[14:15], 0
.LBB0_517:
	v_lshl_add_u64 v[60:61], v[58:59], 0, s[14:15]
	v_add_co_u32_e32 v40, vcc, 0x10c00000, v60
	v_lshlrev_b32_e32 v63, 16, v28
	s_nop 0
	v_addc_co_u32_e32 v41, vcc, 0, v61, vcc
	v_lshlrev_b32_e32 v62, 16, v32
	v_pk_mul_f32 v[64:65], v[48:49], v[62:63]
	v_and_b32_e32 v71, 0xffff0000, v30
	v_add_f32_e32 v1, v24, v65
	v_add_f32_e32 v1, v64, v1
	v_and_b32_e32 v65, 0xffff0000, v28
	v_and_b32_e32 v64, 0xffff0000, v32
	v_pk_mul_f32 v[66:67], v[8:9], v[64:65]
	v_lshlrev_b32_e32 v32, 16, v34
	v_add_f32_e32 v28, v25, v67
	v_add_f32_e32 v63, v66, v28
	v_lshlrev_b32_e32 v67, 16, v29
	v_lshlrev_b32_e32 v66, 16, v33
	v_pk_mul_f32 v[68:69], v[50:51], v[66:67]
	v_and_b32_e32 v70, 0xffff0000, v34
	v_add_f32_e32 v28, v26, v69
	v_add_f32_e32 v65, v68, v28
	v_and_b32_e32 v69, 0xffff0000, v29
	v_and_b32_e32 v68, 0xffff0000, v33
	v_pk_mul_f32 v[28:29], v[10:11], v[68:69]
	v_lshlrev_b32_e32 v33, 16, v30
	v_add_f32_e32 v29, v27, v29
	v_add_f32_e32 v67, v28, v29
	v_pk_mul_f32 v[28:29], v[52:53], v[32:33]
	v_lshlrev_b32_e32 v73, 16, v31
	v_add_f32_e32 v29, v20, v29
	v_add_f32_e32 v33, v28, v29
	v_pk_mul_f32 v[28:29], v[4:5], v[70:71]
	v_lshlrev_b32_e32 v72, 16, v35
	v_add_f32_e32 v29, v21, v29
	v_add_f32_e32 v30, v28, v29
	v_pk_mul_f32 v[28:29], v[54:55], v[72:73]
	v_and_b32_e32 v79, 0xffff0000, v31
	v_add_f32_e32 v29, v22, v29
	v_and_b32_e32 v78, 0xffff0000, v35
	v_add_f32_e32 v34, v28, v29
	v_pk_mul_f32 v[28:29], v[6:7], v[78:79]
	v_lshlrev_b32_e32 v75, 16, v36
	v_add_f32_e32 v29, v23, v29
	v_add_f32_e32 v31, v28, v29
	v_and_b32_e32 v77, 0xffff0000, v36
	v_lshlrev_b32_e32 v81, 16, v37
	v_and_b32_e32 v37, 0xffff0000, v37
	v_lshlrev_b32_e32 v83, 16, v38
	v_and_b32_e32 v85, 0xffff0000, v38
	v_lshlrev_b32_e32 v87, 16, v39
	v_and_b32_e32 v39, 0xffff0000, v39
	s_mov_b32 s16, 0x14c01000
	s_add_u32 s14, s14, 0x4000
	s_addc_u32 s15, s15, 0
	s_cmp_eq_u32 s14, 0x10000
	s_cbranch_scc1 .Lcv2_last0
	s_waitcnt vmcnt(7)
	v_mov_b64_e32 v[40:41], v[100:101]
	v_mov_b64_e32 v[42:43], v[102:103]
	v_add_co_u32_e32 v116, vcc, 0x10c04000, v60
	s_nop 1
	v_addc_co_u32_e32 v117, vcc, 0, v61, vcc
	global_load_dwordx4 v[100:103], v[116:117], off
	s_branch .Lcv2_join0
.Lcv2_last0:
	s_waitcnt vmcnt(7)
	v_mov_b64_e32 v[40:41], v[100:101]
	v_mov_b64_e32 v[42:43], v[102:103]
.Lcv2_join0:
	v_lshlrev_b32_e32 v74, 16, v40
	v_pk_mul_f32 v[28:29], v[56:57], v[74:75]
	v_and_b32_e32 v76, 0xffff0000, v40
	v_add_f32_e32 v1, v29, v1
	v_add_f32_e32 v1, v28, v1
	v_pk_mul_f32 v[28:29], v[12:13], v[76:77]
	v_lshlrev_b32_e32 v80, 16, v41
	v_add_f32_e32 v29, v29, v63
	v_add_f32_e32 v35, v28, v29
	v_pk_mul_f32 v[28:29], v[44:45], v[80:81]
	v_and_b32_e32 v36, 0xffff0000, v41
	v_add_f32_e32 v29, v29, v65
	v_add_f32_e32 v40, v28, v29
	v_pk_mul_f32 v[28:29], v[14:15], v[36:37]
	v_lshlrev_b32_e32 v82, 16, v42
	v_add_f32_e32 v29, v29, v67
	v_add_f32_e32 v41, v28, v29
	v_pk_mul_f32 v[28:29], v[46:47], v[82:83]
	v_and_b32_e32 v84, 0xffff0000, v42
	v_add_f32_e32 v29, v29, v33
	v_add_f32_e32 v33, v28, v29
	v_pk_mul_f32 v[28:29], v[16:17], v[84:85]
	v_lshlrev_b32_e32 v86, 16, v43
	v_add_f32_e32 v29, v29, v30
	v_add_f32_e32 v30, v28, v29
	v_pk_mul_f32 v[28:29], v[2:3], v[86:87]
	v_and_b32_e32 v38, 0xffff0000, v43
	v_add_f32_e32 v29, v29, v34
	v_add_f32_e32 v34, v28, v29
	v_pk_mul_f32 v[28:29], v[18:19], v[38:39]
	v_mov_b32_e32 v43, v76
	v_add_f32_e32 v29, v29, v31
	v_add_f32_e32 v31, v28, v29
	v_cvt_pk_bf16_f32 v28, v1, v35
	v_cvt_pk_bf16_f32 v29, v40, v41
	v_cvt_pk_bf16_f32 v30, v33, v30
	v_cvt_pk_bf16_f32 v31, v34, v31
	v_add_co_u32_e32 v34, vcc, s16, v60
	s_mov_b32 s16, 0x10c02000
	s_nop 0
	v_addc_co_u32_e32 v35, vcc, 0, v61, vcc
	v_add_co_u32_e32 v88, vcc, s16, v60
	global_store_dwordx4 v[34:35], v[28:31], off offset:-4096
	s_nop 0
	v_addc_co_u32_e32 v89, vcc, 0, v61, vcc
	v_mov_b32_e32 v40, v75
	v_mov_b32_e32 v41, v62
	v_pk_mul_f32 v[40:41], v[48:49], v[40:41]
	v_mov_b32_e32 v63, v80
	v_add_f32_e32 v1, v24, v41
	v_add_f32_e32 v1, v40, v1
	v_mov_b32_e32 v40, v77
	v_mov_b32_e32 v41, v64
	v_pk_mul_f32 v[40:41], v[8:9], v[40:41]
	v_mov_b32_e32 v65, v36
	v_add_f32_e32 v33, v25, v41
	v_add_f32_e32 v62, v40, v33
	v_mov_b32_e32 v40, v81
	v_mov_b32_e32 v41, v66
	v_pk_mul_f32 v[40:41], v[50:51], v[40:41]
	v_mov_b32_e32 v67, v82
	v_add_f32_e32 v33, v26, v41
	v_add_f32_e32 v64, v40, v33
	v_mov_b32_e32 v40, v37
	v_mov_b32_e32 v41, v68
	v_pk_mul_f32 v[40:41], v[10:11], v[40:41]
	v_mov_b32_e32 v69, v84
	v_add_f32_e32 v33, v27, v41
	v_add_f32_e32 v66, v40, v33
	v_mov_b32_e32 v40, v83
	v_mov_b32_e32 v41, v32
	v_pk_mul_f32 v[32:33], v[52:53], v[40:41]
	v_mov_b32_e32 v41, v74
	v_add_f32_e32 v33, v20, v33
	v_add_f32_e32 v68, v32, v33
	v_mov_b32_e32 v32, v85
	v_mov_b32_e32 v33, v70
	v_pk_mul_f32 v[32:33], v[4:5], v[32:33]
	v_mov_b32_e32 v71, v86
	v_add_f32_e32 v33, v21, v33
	v_add_f32_e32 v70, v32, v33
	v_mov_b32_e32 v32, v87
	v_mov_b32_e32 v33, v72
	v_pk_mul_f32 v[32:33], v[54:55], v[32:33]
	v_mov_b32_e32 v73, v38
	v_add_f32_e32 v33, v22, v33
	v_add_f32_e32 v72, v32, v33
	v_mov_b32_e32 v32, v39
	v_mov_b32_e32 v33, v78
	v_pk_mul_f32 v[32:33], v[6:7], v[32:33]
	v_pk_mul_f32 v[36:37], v[10:11], v[36:37]
	v_add_f32_e32 v33, v23, v33
	v_add_f32_e32 v78, v32, v33
	v_add_f32_e32 v37, v27, v37
	v_pk_mul_f32 v[74:75], v[48:49], v[74:75]
	s_mov_b32 s16, 0x14c02000
	s_cbranch_scc1 .Lcv2_last1
	s_waitcnt vmcnt(7)
	v_mov_b64_e32 v[28:29], v[104:105]
	v_mov_b64_e32 v[30:31], v[106:107]
	v_add_co_u32_e32 v116, vcc, 0x1000, v116
	s_nop 1
	v_addc_co_u32_e32 v117, vcc, 0, v117, vcc
	global_load_dwordx4 v[104:107], v[116:117], off
	s_branch .Lcv2_join1
; __device__ __forceinline__ unsigned cvt_pk_bf16(float lo, float hi) { unsigned r; asm volatile("v_cvt_pk_bf16_f32 %0, %1, %2" : "=v"(r) : "v"(lo), "v"(hi)); return r; }
; __device__ __forceinline__ float bflo(unsigned w) { return __uint_as_float(w << 16); }
; __device__ __forceinline__ float bfhi(unsigned w) { return __uint_as_float(w & 0xffff0000u); }
; __device__ __forceinline__ float fsilu(float x) { return x * fsigmoid(x); }
; template <bool SILU>
; __device__ __forceinline__ void conv_phase(const bf16_t* src, const float* w, const float* b, bf16_t* dst, int C, int gt, int NGT) {
;     ...
;         for (int r = 0; r < 16; ++r) {
;             const u32x4 x3 = *(const u32x4*)(sp + (size_t)r * C);
;             const unsigned xa[4][4] = {{x0.x, x0.y, x0.z, x0.w}, {x1.x, x1.y, x1.z, x1.w}, {x2.x, x2.y, x2.z, x2.w}, {x3.x, x3.y, x3.z, x3.w}};
;             float a[8];
; #pragma unroll
;             for (int j = 0; j < 8; ++j) a[j] = bs[j];
; #pragma unroll
;             for (int k = 0; k < 4; ++k)
; #pragma unroll
;                 for (int q = 0; q < 4; ++q) { a[2 * q] += wt[k][2 * q] * bflo(xa[k][q]); a[2 * q + 1] += wt[k][2 * q + 1] * bfhi(xa[k][q]); }
;             if (SILU) {
; #pragma unroll
;                 for (int j = 0; j < 8; ++j) a[j] = fsilu(a[j]); }
;             u32x4 o; o.x = cvt_pk_bf16(a[0], a[1]); o.y = cvt_pk_bf16(a[2], a[3]); o.z = cvt_pk_bf16(a[4], a[5]); o.w = cvt_pk_bf16(a[6], a[7]);
;             *(u32x4*)(dst + (size_t)(row0 + r) * C + c0) = o;
.Lcv2_last1:
	s_waitcnt vmcnt(6)
	v_mov_b64_e32 v[28:29], v[104:105]
	v_mov_b64_e32 v[30:31], v[106:107]
.Lcv2_join1:
	v_lshlrev_b32_e32 v40, 16, v28
	v_pk_mul_f32 v[32:33], v[56:57], v[40:41]
	v_and_b32_e32 v42, 0xffff0000, v28
	v_add_f32_e32 v1, v33, v1
	v_add_f32_e32 v1, v32, v1
	v_pk_mul_f32 v[32:33], v[12:13], v[42:43]
	s_nop 0
	v_add_f32_e32 v33, v33, v62
	v_lshlrev_b32_e32 v62, 16, v29
	v_add_f32_e32 v79, v32, v33
	v_pk_mul_f32 v[32:33], v[44:45], v[62:63]
	v_cvt_pk_bf16_f32 v92, v1, v79
	v_add_f32_e32 v1, v24, v75
	v_add_f32_e32 v33, v33, v64
	v_and_b32_e32 v64, 0xffff0000, v29
	v_add_f32_e32 v91, v32, v33
	v_pk_mul_f32 v[32:33], v[14:15], v[64:65]
	v_add_f32_e32 v1, v74, v1
	v_add_f32_e32 v33, v33, v66
	v_lshlrev_b32_e32 v66, 16, v30
	v_add_f32_e32 v93, v32, v33
	v_pk_mul_f32 v[32:33], v[46:47], v[66:67]
	v_cvt_pk_bf16_f32 v93, v91, v93
	v_pk_mul_f32 v[74:75], v[8:9], v[76:77]
	v_add_f32_e32 v33, v33, v68
	v_and_b32_e32 v68, 0xffff0000, v30
	v_add_f32_e32 v94, v32, v33
	v_pk_mul_f32 v[32:33], v[16:17], v[68:69]
	v_add_f32_e32 v75, v25, v75
	v_add_f32_e32 v33, v33, v70
	v_lshlrev_b32_e32 v70, 16, v31
	v_add_f32_e32 v95, v32, v33
	v_pk_mul_f32 v[32:33], v[2:3], v[70:71]
	v_cvt_pk_bf16_f32 v94, v94, v95
	v_add_f32_e32 v76, v74, v75
	v_add_f32_e32 v33, v33, v72
	v_and_b32_e32 v72, 0xffff0000, v31
	v_add_f32_e32 v96, v32, v33
	v_pk_mul_f32 v[32:33], v[18:19], v[72:73]
	v_pk_mul_f32 v[74:75], v[50:51], v[80:81]
	v_add_f32_e32 v33, v33, v78
	v_add_f32_e32 v32, v32, v33
	v_cvt_pk_bf16_f32 v95, v96, v32
	global_store_dwordx4 v[34:35], v[92:95], off
	v_add_f32_e32 v78, v36, v37
	v_pk_mul_f32 v[36:37], v[52:53], v[82:83]
	v_mov_b32_e32 v89, v40
	v_add_f32_e32 v37, v20, v37
	v_add_f32_e32 v79, v36, v37
	v_pk_mul_f32 v[36:37], v[4:5], v[84:85]
	v_add_f32_e32 v75, v26, v75
	v_add_f32_e32 v37, v21, v37
	v_add_f32_e32 v80, v36, v37
	v_pk_mul_f32 v[36:37], v[54:55], v[86:87]
	v_add_f32_e32 v77, v74, v75
	v_add_f32_e32 v37, v22, v37
	v_add_f32_e32 v81, v36, v37
	v_pk_mul_f32 v[36:37], v[6:7], v[38:39]
	v_mov_b32_e32 v75, v42
	v_add_f32_e32 v37, v23, v37
	v_add_f32_e32 v38, v36, v37
	v_mov_b32_e32 v87, v62
	v_mov_b32_e32 v85, v66
	v_mov_b32_e32 v83, v70
	v_add_co_u32_e32 v92, vcc, s16, v60
	v_pk_mul_f32 v[40:41], v[48:49], v[40:41]
	s_nop 0
	v_addc_co_u32_e32 v93, vcc, 0, v61, vcc
	s_cbranch_scc1 .Lcv2_last2
	s_waitcnt vmcnt(7)
	v_mov_b64_e32 v[32:33], v[108:109]
	v_mov_b64_e32 v[34:35], v[110:111]
	v_add_co_u32_e32 v116, vcc, 0x1000, v116
	s_nop 1
	v_addc_co_u32_e32 v117, vcc, 0, v117, vcc
	global_load_dwordx4 v[108:111], v[116:117], off
	s_branch .Lcv2_join2
.Lcv2_last2:
	s_waitcnt vmcnt(5)
	v_mov_b64_e32 v[32:33], v[108:109]
	v_mov_b64_e32 v[34:35], v[110:111]
; __device__ __forceinline__ unsigned cvt_pk_bf16(float lo, float hi) { unsigned r; asm volatile("v_cvt_pk_bf16_f32 %0, %1, %2" : "=v"(r) : "v"(lo), "v"(hi)); return r; }
; template <bool SILU>
; __device__ __forceinline__ void conv_phase(const bf16_t* src, const float* w, const float* b, bf16_t* dst, int C, int gt, int NGT) {
;     ...
;     for (int it = gt; it < nitems; it += NGT) {
;         const int rb = it / c8n, c0 = (it % c8n) * 8, row0 = rb * 16;
;         float wt[4][8], bs[8];
; #pragma unroll
;         for (int k = 0; k < 4; ++k) { const f32x4 w0 = *(const f32x4*)(w + (size_t)k * C + c0), w1 = *(const f32x4*)(w + (size_t)k * C + c0 + 4);
;             wt[k][0] = w0[0]; wt[k][1] = w0[1]; wt[k][2] = w0[2]; wt[k][3] = w0[3]; wt[k][4] = w1[0]; wt[k][5] = w1[1]; wt[k][6] = w1[2]; wt[k][7] = w1[3]; }
;         { const f32x4 b0 = *(const f32x4*)(b + c0), b1 = *(const f32x4*)(b + c0 + 4); bs[0] = b0[0]; bs[1] = b0[1]; bs[2] = b0[2]; bs[3] = b0[3]; bs[4] = b1[0]; bs[5] = b1[1]; bs[6] = b1[2]; bs[7] = b1[3]; }
;         const bool head = (row0 & (SEQ - 1)) == 0;
;         const bf16_t* sp = src + (size_t)row0 * C + c0;
;         u32x4 x0, x1, x2;
;         if (head) { x0 = (u32x4){0u, 0u, 0u, 0u}; x1 = x0; x2 = x0; }
;         else { x0 = *(const u32x4*)(sp - (size_t)3 * C); x1 = *(const u32x4*)(sp - (size_t)2 * C); x2 = *(const u32x4*)(sp - (size_t)C); }
; #pragma unroll 4
;         for (int r = 0; r < 16; ++r) {
;             const u32x4 x3 = *(const u32x4*)(sp + (size_t)r * C);
;             const unsigned xa[4][4] = {{x0.x, x0.y, x0.z, x0.w}, {x1.x, x1.y, x1.z, x1.w}, {x2.x, x2.y, x2.z, x2.w}, {x3.x, x3.y, x3.z, x3.w}};
;             float a[8];
; #pragma unroll
;             for (int j = 0; j < 8; ++j) a[j] = bs[j];
; #pragma unroll
;             for (int k = 0; k < 4; ++k)
; #pragma unroll
;                 for (int q = 0; q < 4; ++q) { a[2 * q] += wt[k][2 * q] * bflo(xa[k][q]); a[2 * q + 1] += wt[k][2 * q + 1] * bfhi(xa[k][q]); }
;             if (SILU) {
; #pragma unroll
;                 for (int j = 0; j < 8; ++j) a[j] = fsilu(a[j]); }
;             u32x4 o; o.x = cvt_pk_bf16(a[0], a[1]); o.y = cvt_pk_bf16(a[2], a[3]); o.z = cvt_pk_bf16(a[4], a[5]); o.w = cvt_pk_bf16(a[6], a[7]);
;             *(u32x4*)(dst + (size_t)(row0 + r) * C + c0) = o;
;             x0 = x1; x1 = x2; x2 = x3;
;         }
.Lcv2_join2:
	v_lshlrev_b32_e32 v88, 16, v32
	v_pk_mul_f32 v[36:37], v[56:57], v[88:89]
	v_and_b32_e32 v74, 0xffff0000, v32
	v_add_f32_e32 v1, v37, v1
	v_add_f32_e32 v1, v36, v1
	v_pk_mul_f32 v[36:37], v[12:13], v[74:75]
	v_lshlrev_b32_e32 v86, 16, v33
	v_add_f32_e32 v37, v37, v76
	v_add_f32_e32 v39, v36, v37
	v_pk_mul_f32 v[36:37], v[44:45], v[86:87]
	v_and_b32_e32 v76, 0xffff0000, v33
	v_add_f32_e32 v37, v37, v77
	v_mov_b32_e32 v77, v64
	v_add_f32_e32 v75, v36, v37
	v_pk_mul_f32 v[36:37], v[14:15], v[76:77]
	v_lshlrev_b32_e32 v84, 16, v34
	v_add_f32_e32 v37, v37, v78
	v_add_f32_e32 v77, v36, v37
	v_pk_mul_f32 v[36:37], v[46:47], v[84:85]
	v_and_b32_e32 v78, 0xffff0000, v34
	v_add_f32_e32 v37, v37, v79
	v_mov_b32_e32 v79, v68
	v_add_f32_e32 v85, v36, v37
	v_pk_mul_f32 v[36:37], v[16:17], v[78:79]
	v_lshlrev_b32_e32 v82, 16, v35
	v_add_f32_e32 v37, v37, v80
	v_add_f32_e32 v79, v36, v37
	v_pk_mul_f32 v[36:37], v[2:3], v[82:83]
	v_and_b32_e32 v80, 0xffff0000, v35
	v_add_f32_e32 v37, v37, v81
	v_mov_b32_e32 v81, v72
	v_add_f32_e32 v83, v36, v37
	v_pk_mul_f32 v[36:37], v[18:19], v[80:81]
	s_nop 0
	v_add_f32_e32 v37, v37, v38
	v_add_f32_e32 v81, v36, v37
	v_cvt_pk_bf16_f32 v36, v1, v39
	v_cvt_pk_bf16_f32 v37, v75, v77
	v_cvt_pk_bf16_f32 v38, v85, v79
	v_cvt_pk_bf16_f32 v39, v83, v81
	global_store_dwordx4 v[92:93], v[36:39], off
	v_add_f32_e32 v1, v24, v41
	v_add_f32_e32 v1, v40, v1
	v_add_co_u32_e32 v36, vcc, s23, v60
	v_pk_mul_f32 v[40:41], v[8:9], v[42:43]
	s_nop 0
	v_addc_co_u32_e32 v37, vcc, 0, v61, vcc
	v_add_f32_e32 v41, v25, v41
	v_add_f32_e32 v42, v40, v41
	v_pk_mul_f32 v[40:41], v[50:51], v[62:63]
	v_add_co_u32_e32 v60, vcc, 0x14c03000, v60
	v_add_f32_e32 v41, v26, v41
	v_add_f32_e32 v43, v40, v41
	v_pk_mul_f32 v[40:41], v[10:11], v[64:65]
	v_addc_co_u32_e32 v61, vcc, 0, v61, vcc
	v_add_f32_e32 v41, v27, v41
	v_add_f32_e32 v62, v40, v41
	v_pk_mul_f32 v[40:41], v[52:53], v[66:67]
	s_nop 0
	v_add_f32_e32 v41, v20, v41
	v_add_f32_e32 v63, v40, v41
	v_pk_mul_f32 v[40:41], v[4:5], v[68:69]
	s_nop 0
	v_add_f32_e32 v41, v21, v41
	v_add_f32_e32 v64, v40, v41
	v_pk_mul_f32 v[40:41], v[54:55], v[70:71]
	s_nop 0
	v_add_f32_e32 v41, v22, v41
	v_add_f32_e32 v65, v40, v41
	v_pk_mul_f32 v[40:41], v[6:7], v[72:73]
	s_nop 0
	v_add_f32_e32 v41, v23, v41
	v_add_f32_e32 v66, v40, v41
	v_mov_b32_e32 v41, v88
	s_cbranch_scc1 .Lcv2_last3
	s_waitcnt vmcnt(7)
	v_mov_b64_e32 v[36:37], v[112:113]
	v_mov_b64_e32 v[38:39], v[114:115]
	v_add_co_u32_e32 v116, vcc, 0x1000, v116
	s_nop 1
	v_addc_co_u32_e32 v117, vcc, 0, v117, vcc
	global_load_dwordx4 v[112:115], v[116:117], off
	s_branch .Lcv2_join3
.Lcv2_last3:
	s_waitcnt vmcnt(4)
	v_mov_b64_e32 v[36:37], v[112:113]
	v_mov_b64_e32 v[38:39], v[114:115]
.Lcv2_join3:
	v_lshlrev_b32_e32 v40, 16, v36
	v_pk_mul_f32 v[40:41], v[56:57], v[40:41]
	s_nop 0
	v_add_f32_e32 v1, v41, v1
	v_add_f32_e32 v1, v40, v1
	v_and_b32_e32 v40, 0xffff0000, v36
	v_mov_b32_e32 v41, v74
	v_pk_mul_f32 v[40:41], v[12:13], v[40:41]
	s_nop 0
	v_add_f32_e32 v41, v41, v42
	v_add_f32_e32 v42, v40, v41
	v_lshlrev_b32_e32 v40, 16, v37
	v_mov_b32_e32 v41, v86
	v_pk_mul_f32 v[40:41], v[44:45], v[40:41]
	s_nop 0
	v_add_f32_e32 v41, v41, v43
	v_add_f32_e32 v43, v40, v41
	v_and_b32_e32 v40, 0xffff0000, v37
	v_mov_b32_e32 v41, v76
	v_pk_mul_f32 v[40:41], v[14:15], v[40:41]
	s_nop 0
	v_add_f32_e32 v41, v41, v62
	v_add_f32_e32 v62, v40, v41
	v_lshlrev_b32_e32 v40, 16, v38
	v_mov_b32_e32 v41, v84
	v_pk_mul_f32 v[40:41], v[46:47], v[40:41]
	s_nop 0
	v_add_f32_e32 v41, v41, v63
	v_add_f32_e32 v63, v40, v41
	v_and_b32_e32 v40, 0xffff0000, v38
	v_mov_b32_e32 v41, v78
	v_pk_mul_f32 v[40:41], v[16:17], v[40:41]
	s_nop 0
	v_add_f32_e32 v41, v41, v64
	v_add_f32_e32 v64, v40, v41
	v_lshlrev_b32_e32 v40, 16, v39
	v_mov_b32_e32 v41, v82
	v_pk_mul_f32 v[40:41], v[2:3], v[40:41]
	s_nop 0
	v_add_f32_e32 v41, v41, v65
	v_add_f32_e32 v65, v40, v41
	v_and_b32_e32 v40, 0xffff0000, v39
	v_mov_b32_e32 v41, v80
	v_pk_mul_f32 v[40:41], v[18:19], v[40:41]
	s_nop 0
	v_add_f32_e32 v41, v41, v66
	v_add_f32_e32 v66, v40, v41
	v_cvt_pk_bf16_f32 v40, v1, v42
	v_cvt_pk_bf16_f32 v41, v43, v62
	v_cvt_pk_bf16_f32 v42, v63, v64
	v_cvt_pk_bf16_f32 v43, v65, v66
	global_store_dwordx4 v[60:61], v[40:43], off
	s_cbranch_scc0 .LBB0_517
	v_readlane_b32 s14, v254, 43
	v_readlane_b32 s15, v254, 44
	s_nop 0
	v_add_u32_e32 v90, s14, v90
	s_mov_b32 s14, 0x1ffff
	v_cmp_lt_i32_e32 vcc, s14, v90
	s_or_b64 s[10:11], vcc, s[10:11]
	s_andn2_b64 exec, exec, s[10:11]
	s_cbranch_execnz .LBB0_514
